# SwiGLU epilogue stores of the four gate/up GEMM phases use sc1 (act is written once, read next phase: keep L2 for the A/B tiles)
# speedup vs baseline: 1.0161x; 1.0161x over previous
.LBB0_164:
	s_lshl_b32 s11, s18, 8
	v_add_u32_e32 v146, s11, v149
	v_or_b32_e32 v162, 16, v146
	v_ashrrev_i32_e32 v147, 31, v146
	v_ashrrev_i32_e32 v163, 31, v162
	v_lshlrev_b64 v[160:161], 6, v[146:147]
	v_lshlrev_b64 v[162:163], 6, v[162:163]
	v_lshl_add_u64 v[160:161], v[136:137], 0, v[160:161]
	v_lshl_add_u64 v[166:167], v[136:137], 0, v[162:163]
	global_load_dwordx4 v[162:165], v[160:161], off
	s_nop 0
	global_load_dwordx4 v[166:169], v[166:167], off
	v_or_b32_e32 v160, 32, v146
	v_ashrrev_i32_e32 v161, 31, v160
	v_lshlrev_b64 v[160:161], 6, v[160:161]
	v_lshl_add_u64 v[160:161], v[136:137], 0, v[160:161]
	global_load_dwordx4 v[170:173], v[160:161], off
	v_or_b32_e32 v160, 48, v146
	v_ashrrev_i32_e32 v161, 31, v160
	v_lshlrev_b64 v[160:161], 6, v[160:161]
	v_lshl_add_u64 v[160:161], v[136:137], 0, v[160:161]
	global_load_dwordx4 v[174:177], v[160:161], off
	v_and_b32_e32 v148, 64, v158
	v_xor_b32_e32 v147, 16, v158
	v_add_u32_e32 v148, 64, v148
	v_xor_b32_e32 v160, 32, v158
	v_cmp_lt_i32_e32 vcc, v147, v148
	v_lshl_or_b32 v178, s49, 7, v154
	v_ashrrev_i32_e32 v179, 31, v178
	v_cndmask_b32_e32 v147, v158, v147, vcc
	v_cmp_lt_i32_e32 vcc, v160, v148
	s_waitcnt vmcnt(0)
	v_mov_b32_e32 v180, v163
	v_mov_b32_e32 v181, v164
	v_mov_b32_e32 v163, v165
	v_cndmask_b32_e32 v148, v158, v160, vcc
	v_pk_add_f32 v[162:163], v[180:181], v[162:163]
	v_lshlrev_b32_e32 v160, 2, v147
	v_lshlrev_b32_e32 v147, 2, v148
	v_mov_b32_e32 v164, v167
	v_mov_b32_e32 v165, v168
	v_mov_b32_e32 v167, v169
	v_add_f32_e32 v148, v162, v163
	v_mov_b32_e32 v168, v171
	v_mov_b32_e32 v169, v172
	v_mov_b32_e32 v171, v173
	v_pk_add_f32 v[162:163], v[164:165], v[166:167]
	ds_bpermute_b32 v161, v160, v148
	v_mov_b32_e32 v172, v175
	v_mov_b32_e32 v173, v176
	v_mov_b32_e32 v175, v177
	v_pk_add_f32 v[164:165], v[168:169], v[170:171]
	v_add_f32_e32 v162, v162, v163
	v_pk_add_f32 v[166:167], v[172:173], v[174:175]
	v_add_f32_e32 v163, v164, v165
	ds_bpermute_b32 v165, v160, v162
	v_add_f32_e32 v164, v166, v167
	ds_bpermute_b32 v166, v160, v163
	ds_bpermute_b32 v167, v160, v164
	s_waitcnt lgkmcnt(3)
	v_add_f32_e32 v148, v148, v161
	ds_bpermute_b32 v161, v147, v148
	s_waitcnt lgkmcnt(3)
	v_add_f32_e32 v162, v162, v165
	ds_bpermute_b32 v165, v147, v162
	s_waitcnt lgkmcnt(3)
	v_add_f32_e32 v163, v163, v166
	s_waitcnt lgkmcnt(2)
	v_add_f32_e32 v164, v164, v167
	ds_bpermute_b32 v166, v147, v163
	ds_bpermute_b32 v167, v147, v164
	s_waitcnt lgkmcnt(3)
	v_add_f32_e32 v148, v148, v161
	v_fmamk_f32 v148, v148, 0x3a800000, v159
	s_waitcnt lgkmcnt(2)
	v_add_f32_e32 v161, v162, v165
	v_rsq_f32_e32 v162, v148
	s_waitcnt lgkmcnt(1)
	v_add_f32_e32 v163, v163, v166
	s_waitcnt lgkmcnt(0)
	v_add_f32_e32 v164, v164, v167
	v_fmamk_f32 v148, v161, 0x3a800000, v159
	v_fmamk_f32 v161, v163, 0x3a800000, v159
	v_fmamk_f32 v163, v164, 0x3a800000, v159
	v_pk_mul_f32 v[126:127], v[126:127], v[162:163] op_sel_hi:[1,0]
	v_pk_mul_f32 v[124:125], v[124:125], v[162:163] op_sel_hi:[1,0]
	v_pk_mul_f32 v[118:119], v[118:119], v[162:163] op_sel_hi:[1,0]
	v_pk_mul_f32 v[116:117], v[116:117], v[162:163] op_sel_hi:[1,0]
	v_mul_f32_e32 v118, v126, v118
	v_mul_f32_e32 v116, v124, v116
	v_mul_f32_e32 v124, 0xbfb8aa3b, v124
	v_mul_f32_e32 v117, v125, v117
	v_mul_f32_e32 v125, 0xbfb8aa3b, v125
	v_mul_f32_e32 v126, 0xbfb8aa3b, v126
	v_mul_f32_e32 v119, v127, v119
	v_mul_f32_e32 v127, 0xbfb8aa3b, v127
	v_exp_f32_e32 v124, v124
	v_exp_f32_e32 v125, v125
	v_exp_f32_e32 v126, v126
	v_exp_f32_e32 v127, v127
	v_pk_mul_f32 v[120:121], v[120:121], v[162:163] op_sel_hi:[1,0]
	v_pk_mul_f32 v[122:123], v[122:123], v[162:163] op_sel_hi:[1,0]
	v_pk_mul_f32 v[114:115], v[114:115], v[162:163] op_sel_hi:[1,0]
	v_pk_mul_f32 v[112:113], v[112:113], v[162:163] op_sel_hi:[1,0]
	v_mul_f32_e32 v162, 0xbfb8aa3b, v121
	v_add_f32_e32 v124, 1.0, v124
	v_add_f32_e32 v125, 1.0, v125
	v_add_f32_e32 v126, 1.0, v126
	v_exp_f32_e32 v162, v162
	v_add_f32_e32 v127, 1.0, v127
	v_rcp_f32_e32 v124, v124
	v_rcp_f32_e32 v125, v125
	v_rcp_f32_e32 v126, v126
	v_rcp_f32_e32 v127, v127
	v_rsq_f32_e32 v166, v161
	v_mul_f32_e32 v161, 0xbfb8aa3b, v120
	v_exp_f32_e32 v161, v161
	v_add_f32_e32 v162, 1.0, v162
	v_mul_f32_e32 v116, v116, v124
	v_mul_f32_e32 v117, v117, v125
	v_mul_f32_e32 v118, v118, v126
	v_mul_f32_e32 v119, v119, v127
	v_cvt_pk_bf16_f32 v116, v116, v117
	v_cvt_pk_bf16_f32 v117, v118, v119
	v_rcp_f32_e32 v118, v162
	v_add_f32_e32 v161, 1.0, v161
	v_mul_f32_e32 v113, v121, v113
	v_rcp_f32_e32 v161, v161
	v_mul_f32_e32 v113, v113, v118
	v_mul_f32_e32 v118, 0xbfb8aa3b, v122
	v_exp_f32_e32 v119, v118
	v_mul_f32_e32 v118, 0xbfb8aa3b, v123
	v_mul_f32_e32 v112, v120, v112
	v_exp_f32_e32 v120, v118
	v_mul_f32_e32 v112, v112, v161
	v_cvt_pk_bf16_f32 v118, v112, v113
	v_add_f32_e32 v112, 1.0, v119
	v_rcp_f32_e32 v112, v112
	v_add_f32_e32 v113, 1.0, v120
	v_rcp_f32_e32 v113, v113
	v_mul_f32_e32 v114, v122, v114
	v_rsq_f32_e32 v164, v148
	v_mul_f32_e32 v112, v114, v112
	v_mul_f32_e32 v114, v123, v115
	v_mul_f32_e32 v113, v114, v113
	v_cvt_pk_bf16_f32 v119, v112, v113
	v_mov_b64_e32 v[112:113], s[36:37]
	v_mad_i64_i32 v[120:121], s[22:23], v146, s48, v[112:113]
	v_lshlrev_b64 v[114:115], 1, v[178:179]
	v_lshl_add_u64 v[120:121], v[120:121], 0, v[114:115]
	v_pk_mul_f32 v[108:109], v[108:109], v[164:165] op_sel_hi:[1,0]
	global_store_dwordx4 v[120:121], v[116:119], off sc1
	v_pk_mul_f32 v[100:101], v[100:101], v[164:165] op_sel_hi:[1,0]
	v_pk_mul_f32 v[110:111], v[110:111], v[164:165] op_sel_hi:[1,0]
	v_pk_mul_f32 v[116:117], v[98:99], v[164:165] op_sel_hi:[1,0]
	v_mul_f32_e32 v98, 0xbfb8aa3b, v108
	v_exp_f32_e32 v119, v98
	v_mul_f32_e32 v98, 0xbfb8aa3b, v109
	v_exp_f32_e32 v120, v98
	v_pk_mul_f32 v[98:99], v[96:97], v[164:165] op_sel_hi:[1,0]
	v_add_f32_e32 v96, 1.0, v119
	v_rcp_f32_e32 v96, v96
	v_add_f32_e32 v97, 1.0, v120
	v_rcp_f32_e32 v97, v97
	v_mul_f32_e32 v100, v108, v100
	v_mul_f32_e32 v96, v100, v96
	v_mul_f32_e32 v100, v109, v101
	v_mul_f32_e32 v97, v100, v97
	v_mul_f32_e32 v100, 0xbfb8aa3b, v110
	v_exp_f32_e32 v100, v100
	v_mul_f32_e32 v101, 0xbfb8aa3b, v111
	v_exp_f32_e32 v101, v101
	v_cvt_pk_bf16_f32 v96, v96, v97
	v_add_f32_e32 v97, 1.0, v100
	v_rcp_f32_e32 v97, v97
	v_add_f32_e32 v100, 1.0, v101
	v_rcp_f32_e32 v100, v100
	v_pk_mul_f32 v[102:103], v[102:103], v[164:165] op_sel_hi:[1,0]
	v_pk_mul_f32 v[104:105], v[104:105], v[164:165] op_sel_hi:[1,0]
	v_mul_f32_e32 v101, v110, v102
	v_mul_f32_e32 v97, v101, v97
	v_mul_f32_e32 v101, v111, v103
	v_mul_f32_e32 v100, v101, v100
	v_mul_f32_e32 v101, 0xbfb8aa3b, v104
	v_exp_f32_e32 v101, v101
	v_mul_f32_e32 v102, 0xbfb8aa3b, v105
	v_exp_f32_e32 v102, v102
	v_cvt_pk_bf16_f32 v97, v97, v100
	v_add_f32_e32 v100, 1.0, v101
	v_rcp_f32_e32 v100, v100
	v_add_f32_e32 v101, 1.0, v102
	v_rcp_f32_e32 v101, v101
	v_pk_mul_f32 v[106:107], v[106:107], v[164:165] op_sel_hi:[1,0]
	v_mul_f32_e32 v98, v104, v98
	v_mul_f32_e32 v98, v98, v100
	v_mul_f32_e32 v99, v105, v99
	v_mul_f32_e32 v100, 0xbfb8aa3b, v106
	v_mul_f32_e32 v99, v99, v101
	v_exp_f32_e32 v100, v100
	v_mul_f32_e32 v101, 0xbfb8aa3b, v107
	v_exp_f32_e32 v101, v101
	v_cvt_pk_bf16_f32 v98, v98, v99
	v_add_f32_e32 v99, 1.0, v100
	v_rcp_f32_e32 v99, v99
	v_add_f32_e32 v100, 1.0, v101
	v_rcp_f32_e32 v100, v100
	v_mul_f32_e32 v101, v106, v116
	v_mul_f32_e32 v99, v101, v99
	v_mul_f32_e32 v101, v107, v117
	v_add_u32_e32 v118, s11, v151
	v_mul_f32_e32 v100, v101, v100
	v_cvt_pk_bf16_f32 v99, v99, v100
	v_mad_i64_i32 v[100:101], s[22:23], v118, s48, v[112:113]
	v_lshl_add_u64 v[100:101], v[100:101], 0, v[114:115]
	v_pk_mul_f32 v[92:93], v[92:93], v[166:167] op_sel_hi:[1,0]
	global_store_dwordx4 v[100:101], v[96:99], off sc1
	v_pk_mul_f32 v[84:85], v[84:85], v[166:167] op_sel_hi:[1,0]
	v_pk_mul_f32 v[94:95], v[94:95], v[166:167] op_sel_hi:[1,0]
	v_pk_mul_f32 v[96:97], v[82:83], v[166:167] op_sel_hi:[1,0]
	v_mul_f32_e32 v82, 0xbfb8aa3b, v92
	v_exp_f32_e32 v99, v82
	v_mul_f32_e32 v82, 0xbfb8aa3b, v93
	v_exp_f32_e32 v100, v82
	v_pk_mul_f32 v[82:83], v[80:81], v[166:167] op_sel_hi:[1,0]
	v_add_f32_e32 v80, 1.0, v99
	v_rcp_f32_e32 v80, v80
	v_add_f32_e32 v81, 1.0, v100
	v_rcp_f32_e32 v81, v81
	v_mul_f32_e32 v84, v92, v84
	v_mul_f32_e32 v80, v84, v80
	v_mul_f32_e32 v84, v93, v85
	v_mul_f32_e32 v81, v84, v81
	v_mul_f32_e32 v84, 0xbfb8aa3b, v94
	v_exp_f32_e32 v84, v84
	v_mul_f32_e32 v85, 0xbfb8aa3b, v95
	v_exp_f32_e32 v85, v85
	v_cvt_pk_bf16_f32 v80, v80, v81
	v_add_f32_e32 v81, 1.0, v84
	v_rcp_f32_e32 v81, v81
	v_add_f32_e32 v84, 1.0, v85
	v_rcp_f32_e32 v84, v84
	v_pk_mul_f32 v[86:87], v[86:87], v[166:167] op_sel_hi:[1,0]
	v_pk_mul_f32 v[88:89], v[88:89], v[166:167] op_sel_hi:[1,0]
	v_mul_f32_e32 v85, v94, v86
	v_mul_f32_e32 v81, v85, v81
	v_mul_f32_e32 v85, v95, v87
	v_mul_f32_e32 v84, v85, v84
	v_mul_f32_e32 v85, 0xbfb8aa3b, v88
	v_exp_f32_e32 v85, v85
	v_mul_f32_e32 v86, 0xbfb8aa3b, v89
	v_exp_f32_e32 v86, v86
	v_cvt_pk_bf16_f32 v81, v81, v84
	v_add_f32_e32 v84, 1.0, v85
	v_rcp_f32_e32 v84, v84
	v_add_f32_e32 v85, 1.0, v86
	v_rcp_f32_e32 v85, v85
	v_pk_mul_f32 v[90:91], v[90:91], v[166:167] op_sel_hi:[1,0]
	v_mul_f32_e32 v82, v88, v82
	v_mul_f32_e32 v82, v82, v84
	v_mul_f32_e32 v83, v89, v83
	v_mul_f32_e32 v84, 0xbfb8aa3b, v90
	v_mul_f32_e32 v83, v83, v85
	v_exp_f32_e32 v84, v84
	v_mul_f32_e32 v85, 0xbfb8aa3b, v91
	v_exp_f32_e32 v85, v85
	v_cvt_pk_bf16_f32 v82, v82, v83
	v_add_f32_e32 v83, 1.0, v84
	v_rcp_f32_e32 v83, v83
	v_add_f32_e32 v84, 1.0, v85
	v_rcp_f32_e32 v84, v84
	v_rsq_f32_e32 v148, v163
	v_mul_f32_e32 v85, v90, v96
	v_mul_f32_e32 v83, v85, v83
	v_mul_f32_e32 v85, v91, v97
	v_add_u32_e32 v98, s11, v152
	v_mul_f32_e32 v84, v85, v84
	v_cvt_pk_bf16_f32 v83, v83, v84
	v_mad_i64_i32 v[84:85], s[22:23], v98, s48, v[112:113]
	v_lshl_add_u64 v[84:85], v[84:85], 0, v[114:115]
	v_pk_mul_f32 v[76:77], v[76:77], v[148:149] op_sel_hi:[1,0]
	global_store_dwordx4 v[84:85], v[80:83], off sc1
	v_pk_mul_f32 v[68:69], v[68:69], v[148:149] op_sel_hi:[1,0]
	v_pk_mul_f32 v[78:79], v[78:79], v[148:149] op_sel_hi:[1,0]
	v_pk_mul_f32 v[80:81], v[66:67], v[148:149] op_sel_hi:[1,0]
	v_mul_f32_e32 v66, 0xbfb8aa3b, v76
	v_exp_f32_e32 v83, v66
	v_mul_f32_e32 v66, 0xbfb8aa3b, v77
	v_exp_f32_e32 v84, v66
	v_pk_mul_f32 v[66:67], v[64:65], v[148:149] op_sel_hi:[1,0]
	v_add_f32_e32 v64, 1.0, v83
	v_rcp_f32_e32 v64, v64
	v_add_f32_e32 v65, 1.0, v84
	v_rcp_f32_e32 v65, v65
	v_mul_f32_e32 v68, v76, v68
	v_mul_f32_e32 v64, v68, v64
	v_mul_f32_e32 v68, v77, v69
	v_mul_f32_e32 v65, v68, v65
	v_mul_f32_e32 v68, 0xbfb8aa3b, v78
	v_exp_f32_e32 v68, v68
	v_mul_f32_e32 v69, 0xbfb8aa3b, v79
	v_exp_f32_e32 v69, v69
	v_cvt_pk_bf16_f32 v64, v64, v65
	v_add_f32_e32 v65, 1.0, v68
	v_rcp_f32_e32 v65, v65
	v_add_f32_e32 v68, 1.0, v69
	v_rcp_f32_e32 v68, v68
	v_pk_mul_f32 v[70:71], v[70:71], v[148:149] op_sel_hi:[1,0]
	v_pk_mul_f32 v[72:73], v[72:73], v[148:149] op_sel_hi:[1,0]
	v_mul_f32_e32 v69, v78, v70
	v_mul_f32_e32 v65, v69, v65
	v_mul_f32_e32 v69, v79, v71
	v_mul_f32_e32 v68, v69, v68
	v_mul_f32_e32 v69, 0xbfb8aa3b, v72
	v_exp_f32_e32 v69, v69
	v_mul_f32_e32 v70, 0xbfb8aa3b, v73
	v_exp_f32_e32 v70, v70
	v_cvt_pk_bf16_f32 v65, v65, v68
	v_add_f32_e32 v68, 1.0, v69
	v_rcp_f32_e32 v68, v68
	v_add_f32_e32 v69, 1.0, v70
	v_rcp_f32_e32 v69, v69
	v_pk_mul_f32 v[74:75], v[74:75], v[148:149] op_sel_hi:[1,0]
	v_mul_f32_e32 v66, v72, v66
	v_mul_f32_e32 v66, v66, v68
	v_mul_f32_e32 v67, v73, v67
	v_mul_f32_e32 v68, 0xbfb8aa3b, v74
	v_mul_f32_e32 v67, v67, v69
	v_exp_f32_e32 v68, v68
	v_mul_f32_e32 v69, 0xbfb8aa3b, v75
	v_exp_f32_e32 v69, v69
	v_cvt_pk_bf16_f32 v66, v66, v67
	v_add_f32_e32 v67, 1.0, v68
	v_rcp_f32_e32 v67, v67
	v_add_f32_e32 v68, 1.0, v69
	v_rcp_f32_e32 v68, v68
	v_mul_f32_e32 v69, v74, v80
	v_mul_f32_e32 v67, v69, v67
	v_mul_f32_e32 v69, v75, v81
	v_add_u32_e32 v82, s11, v153
	v_mul_f32_e32 v68, v69, v68
	v_cvt_pk_bf16_f32 v67, v67, v68
	v_mad_i64_i32 v[68:69], s[22:23], v82, s48, v[112:113]
	v_add_u32_e32 v88, 0x80, v146
	v_lshl_add_u64 v[68:69], v[68:69], 0, v[114:115]
	v_ashrrev_i32_e32 v89, 31, v88
	global_store_dwordx4 v[68:69], v[64:67], off sc1
	v_add_u32_e32 v70, 0x90, v146
	v_ashrrev_i32_e32 v71, 31, v70
	v_lshlrev_b64 v[64:65], 6, v[88:89]
	v_lshl_add_u64 v[64:65], v[136:137], 0, v[64:65]
	global_load_dwordx4 v[72:75], v[64:65], off
	v_lshlrev_b64 v[64:65], 6, v[70:71]
	v_lshl_add_u64 v[64:65], v[136:137], 0, v[64:65]
	global_load_dwordx4 v[76:79], v[64:65], off
	v_add_u32_e32 v66, 0xa0, v146
	v_ashrrev_i32_e32 v67, 31, v66
	v_lshlrev_b64 v[64:65], 6, v[66:67]
	v_lshl_add_u64 v[64:65], v[136:137], 0, v[64:65]
	global_load_dwordx4 v[80:83], v[64:65], off
	v_add_u32_e32 v64, 0xb0, v146
	v_ashrrev_i32_e32 v65, 31, v64
	v_lshlrev_b64 v[68:69], 6, v[64:65]
	v_lshl_add_u64 v[68:69], v[136:137], 0, v[68:69]
	global_load_dwordx4 v[84:87], v[68:69], off
	s_andn2_b64 vcc, exec, s[0:1]
	s_mov_b64 s[0:1], -1
	s_waitcnt vmcnt(3)
	v_mov_b32_e32 v68, v73
	v_mov_b32_e32 v69, v74
	v_mov_b32_e32 v73, v75
	v_pk_add_f32 v[68:69], v[68:69], v[72:73]
	s_nop 0
	v_add_f32_e32 v65, v68, v69
	ds_bpermute_b32 v67, v160, v65
	s_waitcnt vmcnt(2)
	v_mov_b32_e32 v68, v77
	v_mov_b32_e32 v69, v78
	v_mov_b32_e32 v77, v79
	v_pk_add_f32 v[68:69], v[68:69], v[76:77]
	s_waitcnt lgkmcnt(0)
	v_add_f32_e32 v65, v65, v67
	ds_bpermute_b32 v67, v147, v65
	v_add_f32_e32 v68, v68, v69
	ds_bpermute_b32 v69, v160, v68
	s_waitcnt lgkmcnt(1)
	v_add_f32_e32 v65, v65, v67
	v_fmamk_f32 v65, v65, 0x3a800000, v159
	v_rsq_f32_e32 v72, v65
	s_waitcnt lgkmcnt(0)
	v_add_f32_e32 v65, v68, v69
	s_waitcnt vmcnt(1)
	v_mov_b32_e32 v68, v81
	v_mov_b32_e32 v69, v82
	v_mov_b32_e32 v81, v83
	v_pk_add_f32 v[68:69], v[68:69], v[80:81]
	ds_bpermute_b32 v67, v147, v65
	v_add_f32_e32 v71, v68, v69
	s_waitcnt vmcnt(0)
	v_mov_b32_e32 v68, v85
	v_mov_b32_e32 v69, v86
	v_mov_b32_e32 v85, v87
	ds_bpermute_b32 v73, v160, v71
	v_pk_add_f32 v[68:69], v[68:69], v[84:85]
	s_waitcnt lgkmcnt(1)
	v_add_f32_e32 v65, v65, v67
	v_add_f32_e32 v68, v68, v69
	ds_bpermute_b32 v69, v160, v68
	s_waitcnt lgkmcnt(1)
	v_add_f32_e32 v67, v71, v73
	ds_bpermute_b32 v71, v147, v67
	v_fmamk_f32 v65, v65, 0x3a800000, v159
	v_rsq_f32_e32 v74, v65
	s_waitcnt lgkmcnt(1)
	v_add_f32_e32 v68, v68, v69
	ds_bpermute_b32 v69, v147, v68
	s_waitcnt lgkmcnt(1)
	v_add_f32_e32 v65, v67, v71
	v_fmamk_f32 v65, v65, 0x3a800000, v159
	v_rsq_f32_e32 v76, v65
	v_pk_mul_f32 v[60:61], v[60:61], v[72:73] op_sel_hi:[1,0]
	s_waitcnt lgkmcnt(0)
	v_add_f32_e32 v65, v68, v69
	v_fmamk_f32 v65, v65, 0x3a800000, v159
	v_pk_mul_f32 v[78:79], v[50:51], v[72:73] op_sel_hi:[1,0]
	v_mul_f32_e32 v50, 0xbfb8aa3b, v60
	v_rsq_f32_e32 v68, v65
	v_exp_f32_e32 v65, v50
	v_mul_f32_e32 v50, 0xbfb8aa3b, v61
	v_exp_f32_e32 v67, v50
	v_pk_mul_f32 v[50:51], v[48:49], v[72:73] op_sel_hi:[1,0]
	v_add_f32_e32 v48, 1.0, v65
	v_rcp_f32_e32 v48, v48
	v_add_f32_e32 v49, 1.0, v67
	v_rcp_f32_e32 v49, v49
	v_pk_mul_f32 v[52:53], v[52:53], v[72:73] op_sel_hi:[1,0]
	v_pk_mul_f32 v[62:63], v[62:63], v[72:73] op_sel_hi:[1,0]
	v_mul_f32_e32 v52, v60, v52
	v_mul_f32_e32 v48, v52, v48
	v_mul_f32_e32 v52, v61, v53
	v_mul_f32_e32 v49, v52, v49
	v_mul_f32_e32 v52, 0xbfb8aa3b, v62
	v_exp_f32_e32 v52, v52
	v_mul_f32_e32 v53, 0xbfb8aa3b, v63
	v_exp_f32_e32 v53, v53
	v_cvt_pk_bf16_f32 v48, v48, v49
	v_add_f32_e32 v49, 1.0, v52
	v_rcp_f32_e32 v49, v49
	v_add_f32_e32 v52, 1.0, v53
	v_rcp_f32_e32 v52, v52
	v_pk_mul_f32 v[54:55], v[54:55], v[72:73] op_sel_hi:[1,0]
	v_pk_mul_f32 v[56:57], v[56:57], v[72:73] op_sel_hi:[1,0]
	v_mul_f32_e32 v53, v62, v54
	v_mul_f32_e32 v49, v53, v49
	v_mul_f32_e32 v53, v63, v55
	v_mul_f32_e32 v52, v53, v52
	v_mul_f32_e32 v53, 0xbfb8aa3b, v56
	v_exp_f32_e32 v53, v53
	v_mul_f32_e32 v54, 0xbfb8aa3b, v57
	v_exp_f32_e32 v54, v54
	v_cvt_pk_bf16_f32 v49, v49, v52
	v_add_f32_e32 v52, 1.0, v53
	v_rcp_f32_e32 v52, v52
	v_add_f32_e32 v53, 1.0, v54
	v_rcp_f32_e32 v53, v53
	v_pk_mul_f32 v[58:59], v[58:59], v[72:73] op_sel_hi:[1,0]
	v_mul_f32_e32 v50, v56, v50
	v_mul_f32_e32 v50, v50, v52
	v_mul_f32_e32 v51, v57, v51
	v_mul_f32_e32 v52, 0xbfb8aa3b, v58
	v_mul_f32_e32 v51, v51, v53
	v_exp_f32_e32 v52, v52
	v_mul_f32_e32 v53, 0xbfb8aa3b, v59
	v_exp_f32_e32 v53, v53
	v_cvt_pk_bf16_f32 v50, v50, v51
	v_add_f32_e32 v51, 1.0, v52
	v_rcp_f32_e32 v51, v51
	v_add_f32_e32 v52, 1.0, v53
	v_rcp_f32_e32 v52, v52
	v_mul_f32_e32 v53, v58, v78
	v_mul_f32_e32 v51, v53, v51
	v_mul_f32_e32 v53, v59, v79
	v_mul_f32_e32 v52, v53, v52
	v_cvt_pk_bf16_f32 v51, v51, v52
	v_mad_i64_i32 v[52:53], s[22:23], v88, s48, v[112:113]
	v_lshl_add_u64 v[52:53], v[52:53], 0, v[114:115]
	v_pk_mul_f32 v[44:45], v[44:45], v[74:75] op_sel_hi:[1,0]
	global_store_dwordx4 v[52:53], v[48:51], off sc1
	v_pk_mul_f32 v[36:37], v[36:37], v[74:75] op_sel_hi:[1,0]
	v_pk_mul_f32 v[46:47], v[46:47], v[74:75] op_sel_hi:[1,0]
	v_pk_mul_f32 v[48:49], v[34:35], v[74:75] op_sel_hi:[1,0]
	v_mul_f32_e32 v34, 0xbfb8aa3b, v44
	v_exp_f32_e32 v50, v34
	v_mul_f32_e32 v34, 0xbfb8aa3b, v45
	v_exp_f32_e32 v51, v34
	v_pk_mul_f32 v[34:35], v[32:33], v[74:75] op_sel_hi:[1,0]
	v_add_f32_e32 v32, 1.0, v50
	v_rcp_f32_e32 v32, v32
	v_add_f32_e32 v33, 1.0, v51
	v_rcp_f32_e32 v33, v33
	v_mul_f32_e32 v36, v44, v36
	v_mul_f32_e32 v32, v36, v32
	v_mul_f32_e32 v36, v45, v37
	v_mul_f32_e32 v33, v36, v33
	v_mul_f32_e32 v36, 0xbfb8aa3b, v46
	v_exp_f32_e32 v36, v36
	v_mul_f32_e32 v37, 0xbfb8aa3b, v47
	v_exp_f32_e32 v37, v37
	v_cvt_pk_bf16_f32 v32, v32, v33
	v_add_f32_e32 v33, 1.0, v36
	v_rcp_f32_e32 v33, v33
	v_add_f32_e32 v36, 1.0, v37
	v_rcp_f32_e32 v36, v36
	v_pk_mul_f32 v[38:39], v[38:39], v[74:75] op_sel_hi:[1,0]
	v_pk_mul_f32 v[40:41], v[40:41], v[74:75] op_sel_hi:[1,0]
	v_mul_f32_e32 v37, v46, v38
	v_mul_f32_e32 v33, v37, v33
	v_mul_f32_e32 v37, v47, v39
	v_mul_f32_e32 v36, v37, v36
	v_mul_f32_e32 v37, 0xbfb8aa3b, v40
	v_exp_f32_e32 v37, v37
	v_mul_f32_e32 v38, 0xbfb8aa3b, v41
	v_exp_f32_e32 v38, v38
	v_cvt_pk_bf16_f32 v33, v33, v36
	v_add_f32_e32 v36, 1.0, v37
	v_rcp_f32_e32 v36, v36
	v_add_f32_e32 v37, 1.0, v38
	v_rcp_f32_e32 v37, v37
	v_pk_mul_f32 v[42:43], v[42:43], v[74:75] op_sel_hi:[1,0]
	v_mul_f32_e32 v34, v40, v34
	v_mul_f32_e32 v34, v34, v36
	v_mul_f32_e32 v35, v41, v35
	v_mul_f32_e32 v36, 0xbfb8aa3b, v42
	v_mul_f32_e32 v35, v35, v37
	v_exp_f32_e32 v36, v36
	v_mul_f32_e32 v37, 0xbfb8aa3b, v43
	v_exp_f32_e32 v37, v37
	v_cvt_pk_bf16_f32 v34, v34, v35
	v_add_f32_e32 v35, 1.0, v36
	v_rcp_f32_e32 v35, v35
	v_add_f32_e32 v36, 1.0, v37
	v_rcp_f32_e32 v36, v36
	v_mul_f32_e32 v37, v42, v48
	v_mul_f32_e32 v35, v37, v35
	v_mul_f32_e32 v37, v43, v49
	v_mul_f32_e32 v36, v37, v36
	v_cvt_pk_bf16_f32 v35, v35, v36
	v_mad_i64_i32 v[36:37], s[22:23], v70, s48, v[112:113]
	v_lshl_add_u64 v[36:37], v[36:37], 0, v[114:115]
	v_pk_mul_f32 v[28:29], v[28:29], v[76:77] op_sel_hi:[1,0]
	global_store_dwordx4 v[36:37], v[32:35], off sc1
	v_pk_mul_f32 v[20:21], v[20:21], v[76:77] op_sel_hi:[1,0]
	v_pk_mul_f32 v[30:31], v[30:31], v[76:77] op_sel_hi:[1,0]
	v_pk_mul_f32 v[32:33], v[18:19], v[76:77] op_sel_hi:[1,0]
	v_mul_f32_e32 v18, 0xbfb8aa3b, v28
	v_exp_f32_e32 v34, v18
	v_mul_f32_e32 v18, 0xbfb8aa3b, v29
	v_exp_f32_e32 v35, v18
	v_pk_mul_f32 v[18:19], v[16:17], v[76:77] op_sel_hi:[1,0]
	v_add_f32_e32 v16, 1.0, v34
	v_rcp_f32_e32 v16, v16
	v_add_f32_e32 v17, 1.0, v35
	v_rcp_f32_e32 v17, v17
	v_mul_f32_e32 v20, v28, v20
	v_mul_f32_e32 v16, v20, v16
	v_mul_f32_e32 v20, v29, v21
	v_mul_f32_e32 v17, v20, v17
	v_mul_f32_e32 v20, 0xbfb8aa3b, v30
	v_exp_f32_e32 v20, v20
	v_mul_f32_e32 v21, 0xbfb8aa3b, v31
	v_exp_f32_e32 v21, v21
	v_cvt_pk_bf16_f32 v16, v16, v17
	v_add_f32_e32 v17, 1.0, v20
	v_rcp_f32_e32 v17, v17
	v_add_f32_e32 v20, 1.0, v21
	v_rcp_f32_e32 v20, v20
	v_pk_mul_f32 v[22:23], v[22:23], v[76:77] op_sel_hi:[1,0]
	v_pk_mul_f32 v[24:25], v[24:25], v[76:77] op_sel_hi:[1,0]
	v_mul_f32_e32 v21, v30, v22
	v_mul_f32_e32 v17, v21, v17
	v_mul_f32_e32 v21, v31, v23
	v_mul_f32_e32 v20, v21, v20
	v_mul_f32_e32 v21, 0xbfb8aa3b, v24
	v_exp_f32_e32 v21, v21
	v_mul_f32_e32 v22, 0xbfb8aa3b, v25
	v_exp_f32_e32 v22, v22
	v_cvt_pk_bf16_f32 v17, v17, v20
	v_add_f32_e32 v20, 1.0, v21
	v_rcp_f32_e32 v20, v20
	v_add_f32_e32 v21, 1.0, v22
	v_rcp_f32_e32 v21, v21
	v_pk_mul_f32 v[26:27], v[26:27], v[76:77] op_sel_hi:[1,0]
	v_mul_f32_e32 v18, v24, v18
	v_mul_f32_e32 v18, v18, v20
	v_mul_f32_e32 v19, v25, v19
	v_mul_f32_e32 v20, 0xbfb8aa3b, v26
	v_mul_f32_e32 v19, v19, v21
	v_exp_f32_e32 v20, v20
	v_mul_f32_e32 v21, 0xbfb8aa3b, v27
	v_exp_f32_e32 v21, v21
	v_cvt_pk_bf16_f32 v18, v18, v19
	v_add_f32_e32 v19, 1.0, v20
	v_rcp_f32_e32 v19, v19
	v_add_f32_e32 v20, 1.0, v21
	v_rcp_f32_e32 v20, v20
	v_mul_f32_e32 v21, v26, v32
	v_mul_f32_e32 v19, v21, v19
	v_mul_f32_e32 v21, v27, v33
	v_mul_f32_e32 v20, v21, v20
	v_cvt_pk_bf16_f32 v19, v19, v20
	v_mad_i64_i32 v[20:21], s[22:23], v66, s48, v[112:113]
	v_lshl_add_u64 v[20:21], v[20:21], 0, v[114:115]
	v_pk_mul_f32 v[12:13], v[12:13], v[68:69] op_sel_hi:[1,0]
	global_store_dwordx4 v[20:21], v[16:19], off sc1
	v_pk_mul_f32 v[4:5], v[4:5], v[68:69] op_sel_hi:[1,0]
	v_pk_mul_f32 v[14:15], v[14:15], v[68:69] op_sel_hi:[1,0]
	v_pk_mul_f32 v[16:17], v[2:3], v[68:69] op_sel_hi:[1,0]
	v_mul_f32_e32 v2, 0xbfb8aa3b, v12
	v_exp_f32_e32 v18, v2
	v_mul_f32_e32 v2, 0xbfb8aa3b, v13
	v_exp_f32_e32 v19, v2
	v_pk_mul_f32 v[2:3], v[0:1], v[68:69] op_sel_hi:[1,0]
	v_add_f32_e32 v0, 1.0, v18
	v_rcp_f32_e32 v0, v0
	v_add_f32_e32 v1, 1.0, v19
	v_rcp_f32_e32 v1, v1
	v_mul_f32_e32 v4, v12, v4
	v_mul_f32_e32 v0, v4, v0
	v_mul_f32_e32 v4, v13, v5
	v_mul_f32_e32 v1, v4, v1
	v_mul_f32_e32 v4, 0xbfb8aa3b, v14
	v_exp_f32_e32 v4, v4
	v_mul_f32_e32 v5, 0xbfb8aa3b, v15
	v_exp_f32_e32 v5, v5
	v_cvt_pk_bf16_f32 v0, v0, v1
	v_add_f32_e32 v1, 1.0, v4
	v_rcp_f32_e32 v1, v1
	v_add_f32_e32 v4, 1.0, v5
	v_rcp_f32_e32 v4, v4
	v_pk_mul_f32 v[6:7], v[6:7], v[68:69] op_sel_hi:[1,0]
	v_pk_mul_f32 v[8:9], v[8:9], v[68:69] op_sel_hi:[1,0]
	v_mul_f32_e32 v5, v14, v6
	v_mul_f32_e32 v1, v5, v1
	v_mul_f32_e32 v5, v15, v7
	v_mul_f32_e32 v4, v5, v4
	v_mul_f32_e32 v5, 0xbfb8aa3b, v8
	v_exp_f32_e32 v5, v5
	v_mul_f32_e32 v6, 0xbfb8aa3b, v9
	v_exp_f32_e32 v6, v6
	v_cvt_pk_bf16_f32 v1, v1, v4
	v_add_f32_e32 v4, 1.0, v5
	v_rcp_f32_e32 v4, v4
	v_add_f32_e32 v5, 1.0, v6
	v_rcp_f32_e32 v5, v5
	v_pk_mul_f32 v[10:11], v[10:11], v[68:69] op_sel_hi:[1,0]
	v_mul_f32_e32 v2, v8, v2
	v_mul_f32_e32 v2, v2, v4
	v_mul_f32_e32 v3, v9, v3
	v_mul_f32_e32 v4, 0xbfb8aa3b, v10
	v_mul_f32_e32 v3, v3, v5
	v_exp_f32_e32 v4, v4
	v_mul_f32_e32 v5, 0xbfb8aa3b, v11
	v_exp_f32_e32 v5, v5
	v_cvt_pk_bf16_f32 v2, v2, v3
	v_add_f32_e32 v3, 1.0, v4
	v_rcp_f32_e32 v3, v3
	v_add_f32_e32 v4, 1.0, v5
	v_rcp_f32_e32 v4, v4
	v_mul_f32_e32 v5, v10, v16
	v_mul_f32_e32 v3, v5, v3
	v_mul_f32_e32 v5, v11, v17
	v_mul_f32_e32 v4, v5, v4
	v_cvt_pk_bf16_f32 v3, v3, v4
	v_mad_i64_i32 v[4:5], s[22:23], v64, s48, v[112:113]
	v_lshl_add_u64 v[4:5], v[4:5], 0, v[114:115]
	global_store_dwordx4 v[4:5], v[0:3], off sc1
	s_cbranch_vccnz .LBB0_157
	s_andn2_b64 vcc, exec, s[4:5]
	s_cbranch_vccnz .LBB0_156
	s_barrier
	s_branch .LBB0_156

.LBB0_882:
	s_lshl_b32 s11, s18, 8
	v_add_u32_e32 v146, s11, v149
	v_or_b32_e32 v162, 16, v146
	v_ashrrev_i32_e32 v147, 31, v146
	v_ashrrev_i32_e32 v163, 31, v162
	v_lshlrev_b64 v[160:161], 6, v[146:147]
	v_lshlrev_b64 v[162:163], 6, v[162:163]
	v_lshl_add_u64 v[160:161], v[136:137], 0, v[160:161]
	v_lshl_add_u64 v[166:167], v[136:137], 0, v[162:163]
	global_load_dwordx4 v[162:165], v[160:161], off
	s_nop 0
	global_load_dwordx4 v[166:169], v[166:167], off
	v_or_b32_e32 v160, 32, v146
	v_ashrrev_i32_e32 v161, 31, v160
	v_lshlrev_b64 v[160:161], 6, v[160:161]
	v_lshl_add_u64 v[160:161], v[136:137], 0, v[160:161]
	global_load_dwordx4 v[170:173], v[160:161], off
	v_or_b32_e32 v160, 48, v146
	v_ashrrev_i32_e32 v161, 31, v160
	v_lshlrev_b64 v[160:161], 6, v[160:161]
	v_lshl_add_u64 v[160:161], v[136:137], 0, v[160:161]
	global_load_dwordx4 v[174:177], v[160:161], off
	v_and_b32_e32 v148, 64, v158
	v_xor_b32_e32 v147, 16, v158
	v_add_u32_e32 v148, 64, v148
	v_xor_b32_e32 v160, 32, v158
	v_cmp_lt_i32_e32 vcc, v147, v148
	v_lshl_or_b32 v178, s69, 7, v154
	v_ashrrev_i32_e32 v179, 31, v178
	v_cndmask_b32_e32 v147, v158, v147, vcc
	v_cmp_lt_i32_e32 vcc, v160, v148
	s_waitcnt vmcnt(0)
	v_mov_b32_e32 v180, v163
	v_mov_b32_e32 v181, v164
	v_mov_b32_e32 v163, v165
	v_cndmask_b32_e32 v148, v158, v160, vcc
	v_pk_add_f32 v[162:163], v[180:181], v[162:163]
	v_lshlrev_b32_e32 v160, 2, v147
	v_lshlrev_b32_e32 v147, 2, v148
	v_mov_b32_e32 v164, v167
	v_mov_b32_e32 v165, v168
	v_mov_b32_e32 v167, v169
	v_add_f32_e32 v148, v162, v163
	v_mov_b32_e32 v168, v171
	v_mov_b32_e32 v169, v172
	v_mov_b32_e32 v171, v173
	v_pk_add_f32 v[162:163], v[164:165], v[166:167]
	ds_bpermute_b32 v161, v160, v148
	v_mov_b32_e32 v172, v175
	v_mov_b32_e32 v173, v176
	v_mov_b32_e32 v175, v177
	v_pk_add_f32 v[164:165], v[168:169], v[170:171]
	v_add_f32_e32 v162, v162, v163
	v_pk_add_f32 v[166:167], v[172:173], v[174:175]
	v_add_f32_e32 v163, v164, v165
	ds_bpermute_b32 v165, v160, v162
	v_add_f32_e32 v164, v166, v167
	ds_bpermute_b32 v166, v160, v163
	ds_bpermute_b32 v167, v160, v164
	s_waitcnt lgkmcnt(3)
	v_add_f32_e32 v148, v148, v161
	ds_bpermute_b32 v161, v147, v148
	s_waitcnt lgkmcnt(3)
	v_add_f32_e32 v162, v162, v165
	ds_bpermute_b32 v165, v147, v162
	s_waitcnt lgkmcnt(3)
	v_add_f32_e32 v163, v163, v166
	s_waitcnt lgkmcnt(2)
	v_add_f32_e32 v164, v164, v167
	ds_bpermute_b32 v166, v147, v163
	ds_bpermute_b32 v167, v147, v164
	s_waitcnt lgkmcnt(3)
	v_add_f32_e32 v148, v148, v161
	v_fmamk_f32 v148, v148, 0x3a800000, v159
	s_waitcnt lgkmcnt(2)
	v_add_f32_e32 v161, v162, v165
	v_rsq_f32_e32 v162, v148
	s_waitcnt lgkmcnt(1)
	v_add_f32_e32 v163, v163, v166
	s_waitcnt lgkmcnt(0)
	v_add_f32_e32 v164, v164, v167
	v_fmamk_f32 v148, v161, 0x3a800000, v159
	v_fmamk_f32 v161, v163, 0x3a800000, v159
	v_fmamk_f32 v163, v164, 0x3a800000, v159
	v_pk_mul_f32 v[126:127], v[126:127], v[162:163] op_sel_hi:[1,0]
	v_pk_mul_f32 v[124:125], v[124:125], v[162:163] op_sel_hi:[1,0]
	v_pk_mul_f32 v[118:119], v[118:119], v[162:163] op_sel_hi:[1,0]
	v_pk_mul_f32 v[116:117], v[116:117], v[162:163] op_sel_hi:[1,0]
	v_mul_f32_e32 v118, v126, v118
	v_mul_f32_e32 v116, v124, v116
	v_mul_f32_e32 v124, 0xbfb8aa3b, v124
	v_mul_f32_e32 v117, v125, v117
	v_mul_f32_e32 v125, 0xbfb8aa3b, v125
	v_mul_f32_e32 v126, 0xbfb8aa3b, v126
	v_mul_f32_e32 v119, v127, v119
	v_mul_f32_e32 v127, 0xbfb8aa3b, v127
	v_exp_f32_e32 v124, v124
	v_exp_f32_e32 v125, v125
	v_exp_f32_e32 v126, v126
	v_exp_f32_e32 v127, v127
	v_pk_mul_f32 v[120:121], v[120:121], v[162:163] op_sel_hi:[1,0]
	v_pk_mul_f32 v[122:123], v[122:123], v[162:163] op_sel_hi:[1,0]
	v_pk_mul_f32 v[114:115], v[114:115], v[162:163] op_sel_hi:[1,0]
	v_pk_mul_f32 v[112:113], v[112:113], v[162:163] op_sel_hi:[1,0]
	v_mul_f32_e32 v162, 0xbfb8aa3b, v121
	v_add_f32_e32 v124, 1.0, v124
	v_add_f32_e32 v125, 1.0, v125
	v_add_f32_e32 v126, 1.0, v126
	v_exp_f32_e32 v162, v162
	v_add_f32_e32 v127, 1.0, v127
	v_rcp_f32_e32 v124, v124
	v_rcp_f32_e32 v125, v125
	v_rcp_f32_e32 v126, v126
	v_rcp_f32_e32 v127, v127
	v_rsq_f32_e32 v166, v161
	v_mul_f32_e32 v161, 0xbfb8aa3b, v120
	v_exp_f32_e32 v161, v161
	v_add_f32_e32 v162, 1.0, v162
	v_mul_f32_e32 v116, v116, v124
	v_mul_f32_e32 v117, v117, v125
	v_mul_f32_e32 v118, v118, v126
	v_mul_f32_e32 v119, v119, v127
	v_cvt_pk_bf16_f32 v116, v116, v117
	v_cvt_pk_bf16_f32 v117, v118, v119
	v_rcp_f32_e32 v118, v162
	v_add_f32_e32 v161, 1.0, v161
	v_mul_f32_e32 v113, v121, v113
	v_rcp_f32_e32 v161, v161
	v_mul_f32_e32 v113, v113, v118
	v_mul_f32_e32 v118, 0xbfb8aa3b, v122
	v_exp_f32_e32 v119, v118
	v_mul_f32_e32 v118, 0xbfb8aa3b, v123
	v_mul_f32_e32 v112, v120, v112
	v_exp_f32_e32 v120, v118
	v_mul_f32_e32 v112, v112, v161
	v_cvt_pk_bf16_f32 v118, v112, v113
	v_add_f32_e32 v112, 1.0, v119
	v_rcp_f32_e32 v112, v112
	v_add_f32_e32 v113, 1.0, v120
	v_rcp_f32_e32 v113, v113
	v_mul_f32_e32 v114, v122, v114
	v_rsq_f32_e32 v164, v148
	v_mul_f32_e32 v112, v114, v112
	v_mul_f32_e32 v114, v123, v115
	v_mul_f32_e32 v113, v114, v113
	v_cvt_pk_bf16_f32 v119, v112, v113
	v_mov_b64_e32 v[112:113], s[36:37]
	v_mad_i64_i32 v[120:121], s[22:23], v146, s68, v[112:113]
	v_lshlrev_b64 v[114:115], 1, v[178:179]
	v_lshl_add_u64 v[120:121], v[120:121], 0, v[114:115]
	v_pk_mul_f32 v[108:109], v[108:109], v[164:165] op_sel_hi:[1,0]
	global_store_dwordx4 v[120:121], v[116:119], off sc1
	v_pk_mul_f32 v[100:101], v[100:101], v[164:165] op_sel_hi:[1,0]
	v_pk_mul_f32 v[110:111], v[110:111], v[164:165] op_sel_hi:[1,0]
	v_pk_mul_f32 v[116:117], v[98:99], v[164:165] op_sel_hi:[1,0]
	v_mul_f32_e32 v98, 0xbfb8aa3b, v108
	v_exp_f32_e32 v119, v98
	v_mul_f32_e32 v98, 0xbfb8aa3b, v109
	v_exp_f32_e32 v120, v98
	v_pk_mul_f32 v[98:99], v[96:97], v[164:165] op_sel_hi:[1,0]
	v_add_f32_e32 v96, 1.0, v119
	v_rcp_f32_e32 v96, v96
	v_add_f32_e32 v97, 1.0, v120
	v_rcp_f32_e32 v97, v97
	v_mul_f32_e32 v100, v108, v100
	v_mul_f32_e32 v96, v100, v96
	v_mul_f32_e32 v100, v109, v101
	v_mul_f32_e32 v97, v100, v97
	v_mul_f32_e32 v100, 0xbfb8aa3b, v110
	v_exp_f32_e32 v100, v100
	v_mul_f32_e32 v101, 0xbfb8aa3b, v111
	v_exp_f32_e32 v101, v101
	v_cvt_pk_bf16_f32 v96, v96, v97
	v_add_f32_e32 v97, 1.0, v100
	v_rcp_f32_e32 v97, v97
	v_add_f32_e32 v100, 1.0, v101
	v_rcp_f32_e32 v100, v100
	v_pk_mul_f32 v[102:103], v[102:103], v[164:165] op_sel_hi:[1,0]
	v_pk_mul_f32 v[104:105], v[104:105], v[164:165] op_sel_hi:[1,0]
	v_mul_f32_e32 v101, v110, v102
	v_mul_f32_e32 v97, v101, v97
	v_mul_f32_e32 v101, v111, v103
	v_mul_f32_e32 v100, v101, v100
	v_mul_f32_e32 v101, 0xbfb8aa3b, v104
	v_exp_f32_e32 v101, v101
	v_mul_f32_e32 v102, 0xbfb8aa3b, v105
	v_exp_f32_e32 v102, v102
	v_cvt_pk_bf16_f32 v97, v97, v100
	v_add_f32_e32 v100, 1.0, v101
	v_rcp_f32_e32 v100, v100
	v_add_f32_e32 v101, 1.0, v102
	v_rcp_f32_e32 v101, v101
	v_pk_mul_f32 v[106:107], v[106:107], v[164:165] op_sel_hi:[1,0]
	v_mul_f32_e32 v98, v104, v98
	v_mul_f32_e32 v98, v98, v100
	v_mul_f32_e32 v99, v105, v99
	v_mul_f32_e32 v100, 0xbfb8aa3b, v106
	v_mul_f32_e32 v99, v99, v101
	v_exp_f32_e32 v100, v100
	v_mul_f32_e32 v101, 0xbfb8aa3b, v107
	v_exp_f32_e32 v101, v101
	v_cvt_pk_bf16_f32 v98, v98, v99
	v_add_f32_e32 v99, 1.0, v100
	v_rcp_f32_e32 v99, v99
	v_add_f32_e32 v100, 1.0, v101
	v_rcp_f32_e32 v100, v100
	v_mul_f32_e32 v101, v106, v116
	v_mul_f32_e32 v99, v101, v99
	v_mul_f32_e32 v101, v107, v117
	v_add_u32_e32 v118, s11, v151
	v_mul_f32_e32 v100, v101, v100
	v_cvt_pk_bf16_f32 v99, v99, v100
	v_mad_i64_i32 v[100:101], s[22:23], v118, s68, v[112:113]
	v_lshl_add_u64 v[100:101], v[100:101], 0, v[114:115]
	v_pk_mul_f32 v[92:93], v[92:93], v[166:167] op_sel_hi:[1,0]
	global_store_dwordx4 v[100:101], v[96:99], off sc1
	v_pk_mul_f32 v[84:85], v[84:85], v[166:167] op_sel_hi:[1,0]
	v_pk_mul_f32 v[94:95], v[94:95], v[166:167] op_sel_hi:[1,0]
	v_pk_mul_f32 v[96:97], v[82:83], v[166:167] op_sel_hi:[1,0]
	v_mul_f32_e32 v82, 0xbfb8aa3b, v92
	v_exp_f32_e32 v99, v82
	v_mul_f32_e32 v82, 0xbfb8aa3b, v93
	v_exp_f32_e32 v100, v82
	v_pk_mul_f32 v[82:83], v[80:81], v[166:167] op_sel_hi:[1,0]
	v_add_f32_e32 v80, 1.0, v99
	v_rcp_f32_e32 v80, v80
	v_add_f32_e32 v81, 1.0, v100
	v_rcp_f32_e32 v81, v81
	v_mul_f32_e32 v84, v92, v84
	v_mul_f32_e32 v80, v84, v80
	v_mul_f32_e32 v84, v93, v85
	v_mul_f32_e32 v81, v84, v81
	v_mul_f32_e32 v84, 0xbfb8aa3b, v94
	v_exp_f32_e32 v84, v84
	v_mul_f32_e32 v85, 0xbfb8aa3b, v95
	v_exp_f32_e32 v85, v85
	v_cvt_pk_bf16_f32 v80, v80, v81
	v_add_f32_e32 v81, 1.0, v84
	v_rcp_f32_e32 v81, v81
	v_add_f32_e32 v84, 1.0, v85
	v_rcp_f32_e32 v84, v84
	v_pk_mul_f32 v[86:87], v[86:87], v[166:167] op_sel_hi:[1,0]
	v_pk_mul_f32 v[88:89], v[88:89], v[166:167] op_sel_hi:[1,0]
	v_mul_f32_e32 v85, v94, v86
	v_mul_f32_e32 v81, v85, v81
	v_mul_f32_e32 v85, v95, v87
	v_mul_f32_e32 v84, v85, v84
	v_mul_f32_e32 v85, 0xbfb8aa3b, v88
	v_exp_f32_e32 v85, v85
	v_mul_f32_e32 v86, 0xbfb8aa3b, v89
	v_exp_f32_e32 v86, v86
	v_cvt_pk_bf16_f32 v81, v81, v84
	v_add_f32_e32 v84, 1.0, v85
	v_rcp_f32_e32 v84, v84
	v_add_f32_e32 v85, 1.0, v86
	v_rcp_f32_e32 v85, v85
	v_pk_mul_f32 v[90:91], v[90:91], v[166:167] op_sel_hi:[1,0]
	v_mul_f32_e32 v82, v88, v82
	v_mul_f32_e32 v82, v82, v84
	v_mul_f32_e32 v83, v89, v83
	v_mul_f32_e32 v84, 0xbfb8aa3b, v90
	v_mul_f32_e32 v83, v83, v85
	v_exp_f32_e32 v84, v84
	v_mul_f32_e32 v85, 0xbfb8aa3b, v91
	v_exp_f32_e32 v85, v85
	v_cvt_pk_bf16_f32 v82, v82, v83
	v_add_f32_e32 v83, 1.0, v84
	v_rcp_f32_e32 v83, v83
	v_add_f32_e32 v84, 1.0, v85
	v_rcp_f32_e32 v84, v84
	v_rsq_f32_e32 v148, v163
	v_mul_f32_e32 v85, v90, v96
	v_mul_f32_e32 v83, v85, v83
	v_mul_f32_e32 v85, v91, v97
	v_add_u32_e32 v98, s11, v152
	v_mul_f32_e32 v84, v85, v84
	v_cvt_pk_bf16_f32 v83, v83, v84
	v_mad_i64_i32 v[84:85], s[22:23], v98, s68, v[112:113]
	v_lshl_add_u64 v[84:85], v[84:85], 0, v[114:115]
	v_pk_mul_f32 v[76:77], v[76:77], v[148:149] op_sel_hi:[1,0]
	global_store_dwordx4 v[84:85], v[80:83], off sc1
	v_pk_mul_f32 v[68:69], v[68:69], v[148:149] op_sel_hi:[1,0]
	v_pk_mul_f32 v[78:79], v[78:79], v[148:149] op_sel_hi:[1,0]
	v_pk_mul_f32 v[80:81], v[66:67], v[148:149] op_sel_hi:[1,0]
	v_mul_f32_e32 v66, 0xbfb8aa3b, v76
	v_exp_f32_e32 v83, v66
	v_mul_f32_e32 v66, 0xbfb8aa3b, v77
	v_exp_f32_e32 v84, v66
	v_pk_mul_f32 v[66:67], v[64:65], v[148:149] op_sel_hi:[1,0]
	v_add_f32_e32 v64, 1.0, v83
	v_rcp_f32_e32 v64, v64
	v_add_f32_e32 v65, 1.0, v84
	v_rcp_f32_e32 v65, v65
	v_mul_f32_e32 v68, v76, v68
	v_mul_f32_e32 v64, v68, v64
	v_mul_f32_e32 v68, v77, v69
	v_mul_f32_e32 v65, v68, v65
	v_mul_f32_e32 v68, 0xbfb8aa3b, v78
	v_exp_f32_e32 v68, v68
	v_mul_f32_e32 v69, 0xbfb8aa3b, v79
	v_exp_f32_e32 v69, v69
	v_cvt_pk_bf16_f32 v64, v64, v65
	v_add_f32_e32 v65, 1.0, v68
	v_rcp_f32_e32 v65, v65
	v_add_f32_e32 v68, 1.0, v69
	v_rcp_f32_e32 v68, v68
	v_pk_mul_f32 v[70:71], v[70:71], v[148:149] op_sel_hi:[1,0]
	v_pk_mul_f32 v[72:73], v[72:73], v[148:149] op_sel_hi:[1,0]
	v_mul_f32_e32 v69, v78, v70
	v_mul_f32_e32 v65, v69, v65
	v_mul_f32_e32 v69, v79, v71
	v_mul_f32_e32 v68, v69, v68
	v_mul_f32_e32 v69, 0xbfb8aa3b, v72
	v_exp_f32_e32 v69, v69
	v_mul_f32_e32 v70, 0xbfb8aa3b, v73
	v_exp_f32_e32 v70, v70
	v_cvt_pk_bf16_f32 v65, v65, v68
	v_add_f32_e32 v68, 1.0, v69
	v_rcp_f32_e32 v68, v68
	v_add_f32_e32 v69, 1.0, v70
	v_rcp_f32_e32 v69, v69
	v_pk_mul_f32 v[74:75], v[74:75], v[148:149] op_sel_hi:[1,0]
	v_mul_f32_e32 v66, v72, v66
	v_mul_f32_e32 v66, v66, v68
	v_mul_f32_e32 v67, v73, v67
	v_mul_f32_e32 v68, 0xbfb8aa3b, v74
	v_mul_f32_e32 v67, v67, v69
	v_exp_f32_e32 v68, v68
	v_mul_f32_e32 v69, 0xbfb8aa3b, v75
	v_exp_f32_e32 v69, v69
	v_cvt_pk_bf16_f32 v66, v66, v67
	v_add_f32_e32 v67, 1.0, v68
	v_rcp_f32_e32 v67, v67
	v_add_f32_e32 v68, 1.0, v69
	v_rcp_f32_e32 v68, v68
	v_mul_f32_e32 v69, v74, v80
	v_mul_f32_e32 v67, v69, v67
	v_mul_f32_e32 v69, v75, v81
	v_add_u32_e32 v82, s11, v153
	v_mul_f32_e32 v68, v69, v68
	v_cvt_pk_bf16_f32 v67, v67, v68
	v_mad_i64_i32 v[68:69], s[22:23], v82, s68, v[112:113]
	v_add_u32_e32 v88, 0x80, v146
	v_lshl_add_u64 v[68:69], v[68:69], 0, v[114:115]
	v_ashrrev_i32_e32 v89, 31, v88
	global_store_dwordx4 v[68:69], v[64:67], off sc1
	v_add_u32_e32 v70, 0x90, v146
	v_ashrrev_i32_e32 v71, 31, v70
	v_lshlrev_b64 v[64:65], 6, v[88:89]
	v_lshl_add_u64 v[64:65], v[136:137], 0, v[64:65]
	global_load_dwordx4 v[72:75], v[64:65], off
	v_lshlrev_b64 v[64:65], 6, v[70:71]
	v_lshl_add_u64 v[64:65], v[136:137], 0, v[64:65]
	global_load_dwordx4 v[76:79], v[64:65], off
	v_add_u32_e32 v66, 0xa0, v146
	v_ashrrev_i32_e32 v67, 31, v66
	v_lshlrev_b64 v[64:65], 6, v[66:67]
	v_lshl_add_u64 v[64:65], v[136:137], 0, v[64:65]
	global_load_dwordx4 v[80:83], v[64:65], off
	v_add_u32_e32 v64, 0xb0, v146
	v_ashrrev_i32_e32 v65, 31, v64
	v_lshlrev_b64 v[68:69], 6, v[64:65]
	v_lshl_add_u64 v[68:69], v[136:137], 0, v[68:69]
	global_load_dwordx4 v[84:87], v[68:69], off
	s_andn2_b64 vcc, exec, s[0:1]
	s_mov_b64 s[0:1], -1
	s_waitcnt vmcnt(3)
	v_mov_b32_e32 v68, v73
	v_mov_b32_e32 v69, v74
	v_mov_b32_e32 v73, v75
	v_pk_add_f32 v[68:69], v[68:69], v[72:73]
	s_nop 0
	v_add_f32_e32 v65, v68, v69
	ds_bpermute_b32 v67, v160, v65
	s_waitcnt vmcnt(2)
	v_mov_b32_e32 v68, v77
	v_mov_b32_e32 v69, v78
	v_mov_b32_e32 v77, v79
	v_pk_add_f32 v[68:69], v[68:69], v[76:77]
	s_waitcnt lgkmcnt(0)
	v_add_f32_e32 v65, v65, v67
	ds_bpermute_b32 v67, v147, v65
	v_add_f32_e32 v68, v68, v69
	ds_bpermute_b32 v69, v160, v68
	s_waitcnt lgkmcnt(1)
	v_add_f32_e32 v65, v65, v67
	v_fmamk_f32 v65, v65, 0x3a800000, v159
	v_rsq_f32_e32 v72, v65
	s_waitcnt lgkmcnt(0)
	v_add_f32_e32 v65, v68, v69
	s_waitcnt vmcnt(1)
	v_mov_b32_e32 v68, v81
	v_mov_b32_e32 v69, v82
	v_mov_b32_e32 v81, v83
	v_pk_add_f32 v[68:69], v[68:69], v[80:81]
	ds_bpermute_b32 v67, v147, v65
	v_add_f32_e32 v71, v68, v69
	s_waitcnt vmcnt(0)
	v_mov_b32_e32 v68, v85
	v_mov_b32_e32 v69, v86
	v_mov_b32_e32 v85, v87
	ds_bpermute_b32 v73, v160, v71
	v_pk_add_f32 v[68:69], v[68:69], v[84:85]
	s_waitcnt lgkmcnt(1)
	v_add_f32_e32 v65, v65, v67
	v_add_f32_e32 v68, v68, v69
	ds_bpermute_b32 v69, v160, v68
	s_waitcnt lgkmcnt(1)
	v_add_f32_e32 v67, v71, v73
	ds_bpermute_b32 v71, v147, v67
	v_fmamk_f32 v65, v65, 0x3a800000, v159
	v_rsq_f32_e32 v74, v65
	s_waitcnt lgkmcnt(1)
	v_add_f32_e32 v68, v68, v69
	ds_bpermute_b32 v69, v147, v68
	s_waitcnt lgkmcnt(1)
	v_add_f32_e32 v65, v67, v71
	v_fmamk_f32 v65, v65, 0x3a800000, v159
	v_rsq_f32_e32 v76, v65
	v_pk_mul_f32 v[60:61], v[60:61], v[72:73] op_sel_hi:[1,0]
	s_waitcnt lgkmcnt(0)
	v_add_f32_e32 v65, v68, v69
	v_fmamk_f32 v65, v65, 0x3a800000, v159
	v_pk_mul_f32 v[78:79], v[50:51], v[72:73] op_sel_hi:[1,0]
	v_mul_f32_e32 v50, 0xbfb8aa3b, v60
	v_rsq_f32_e32 v68, v65
	v_exp_f32_e32 v65, v50
	v_mul_f32_e32 v50, 0xbfb8aa3b, v61
	v_exp_f32_e32 v67, v50
	v_pk_mul_f32 v[50:51], v[48:49], v[72:73] op_sel_hi:[1,0]
	v_add_f32_e32 v48, 1.0, v65
	v_rcp_f32_e32 v48, v48
	v_add_f32_e32 v49, 1.0, v67
	v_rcp_f32_e32 v49, v49
	v_pk_mul_f32 v[52:53], v[52:53], v[72:73] op_sel_hi:[1,0]
	v_pk_mul_f32 v[62:63], v[62:63], v[72:73] op_sel_hi:[1,0]
	v_mul_f32_e32 v52, v60, v52
	v_mul_f32_e32 v48, v52, v48
	v_mul_f32_e32 v52, v61, v53
	v_mul_f32_e32 v49, v52, v49
	v_mul_f32_e32 v52, 0xbfb8aa3b, v62
	v_exp_f32_e32 v52, v52
	v_mul_f32_e32 v53, 0xbfb8aa3b, v63
	v_exp_f32_e32 v53, v53
	v_cvt_pk_bf16_f32 v48, v48, v49
	v_add_f32_e32 v49, 1.0, v52
	v_rcp_f32_e32 v49, v49
	v_add_f32_e32 v52, 1.0, v53
	v_rcp_f32_e32 v52, v52
	v_pk_mul_f32 v[54:55], v[54:55], v[72:73] op_sel_hi:[1,0]
	v_pk_mul_f32 v[56:57], v[56:57], v[72:73] op_sel_hi:[1,0]
	v_mul_f32_e32 v53, v62, v54
	v_mul_f32_e32 v49, v53, v49
	v_mul_f32_e32 v53, v63, v55
	v_mul_f32_e32 v52, v53, v52
	v_mul_f32_e32 v53, 0xbfb8aa3b, v56
	v_exp_f32_e32 v53, v53
	v_mul_f32_e32 v54, 0xbfb8aa3b, v57
	v_exp_f32_e32 v54, v54
	v_cvt_pk_bf16_f32 v49, v49, v52
	v_add_f32_e32 v52, 1.0, v53
	v_rcp_f32_e32 v52, v52
	v_add_f32_e32 v53, 1.0, v54
	v_rcp_f32_e32 v53, v53
	v_pk_mul_f32 v[58:59], v[58:59], v[72:73] op_sel_hi:[1,0]
	v_mul_f32_e32 v50, v56, v50
	v_mul_f32_e32 v50, v50, v52
	v_mul_f32_e32 v51, v57, v51
	v_mul_f32_e32 v52, 0xbfb8aa3b, v58
	v_mul_f32_e32 v51, v51, v53
	v_exp_f32_e32 v52, v52
	v_mul_f32_e32 v53, 0xbfb8aa3b, v59
	v_exp_f32_e32 v53, v53
	v_cvt_pk_bf16_f32 v50, v50, v51
	v_add_f32_e32 v51, 1.0, v52
	v_rcp_f32_e32 v51, v51
	v_add_f32_e32 v52, 1.0, v53
	v_rcp_f32_e32 v52, v52
	v_mul_f32_e32 v53, v58, v78
	v_mul_f32_e32 v51, v53, v51
	v_mul_f32_e32 v53, v59, v79
	v_mul_f32_e32 v52, v53, v52
	v_cvt_pk_bf16_f32 v51, v51, v52
	v_mad_i64_i32 v[52:53], s[22:23], v88, s68, v[112:113]
	v_lshl_add_u64 v[52:53], v[52:53], 0, v[114:115]
	v_pk_mul_f32 v[44:45], v[44:45], v[74:75] op_sel_hi:[1,0]
	global_store_dwordx4 v[52:53], v[48:51], off sc1
	v_pk_mul_f32 v[36:37], v[36:37], v[74:75] op_sel_hi:[1,0]
	v_pk_mul_f32 v[46:47], v[46:47], v[74:75] op_sel_hi:[1,0]
	v_pk_mul_f32 v[48:49], v[34:35], v[74:75] op_sel_hi:[1,0]
	v_mul_f32_e32 v34, 0xbfb8aa3b, v44
	v_exp_f32_e32 v50, v34
	v_mul_f32_e32 v34, 0xbfb8aa3b, v45
	v_exp_f32_e32 v51, v34
	v_pk_mul_f32 v[34:35], v[32:33], v[74:75] op_sel_hi:[1,0]
	v_add_f32_e32 v32, 1.0, v50
	v_rcp_f32_e32 v32, v32
	v_add_f32_e32 v33, 1.0, v51
	v_rcp_f32_e32 v33, v33
	v_mul_f32_e32 v36, v44, v36
	v_mul_f32_e32 v32, v36, v32
	v_mul_f32_e32 v36, v45, v37
	v_mul_f32_e32 v33, v36, v33
	v_mul_f32_e32 v36, 0xbfb8aa3b, v46
	v_exp_f32_e32 v36, v36
	v_mul_f32_e32 v37, 0xbfb8aa3b, v47
	v_exp_f32_e32 v37, v37
	v_cvt_pk_bf16_f32 v32, v32, v33
	v_add_f32_e32 v33, 1.0, v36
	v_rcp_f32_e32 v33, v33
	v_add_f32_e32 v36, 1.0, v37
	v_rcp_f32_e32 v36, v36
	v_pk_mul_f32 v[38:39], v[38:39], v[74:75] op_sel_hi:[1,0]
	v_pk_mul_f32 v[40:41], v[40:41], v[74:75] op_sel_hi:[1,0]
	v_mul_f32_e32 v37, v46, v38
	v_mul_f32_e32 v33, v37, v33
	v_mul_f32_e32 v37, v47, v39
	v_mul_f32_e32 v36, v37, v36
	v_mul_f32_e32 v37, 0xbfb8aa3b, v40
	v_exp_f32_e32 v37, v37
	v_mul_f32_e32 v38, 0xbfb8aa3b, v41
	v_exp_f32_e32 v38, v38
	v_cvt_pk_bf16_f32 v33, v33, v36
	v_add_f32_e32 v36, 1.0, v37
	v_rcp_f32_e32 v36, v36
	v_add_f32_e32 v37, 1.0, v38
	v_rcp_f32_e32 v37, v37
	v_pk_mul_f32 v[42:43], v[42:43], v[74:75] op_sel_hi:[1,0]
	v_mul_f32_e32 v34, v40, v34
	v_mul_f32_e32 v34, v34, v36
	v_mul_f32_e32 v35, v41, v35
	v_mul_f32_e32 v36, 0xbfb8aa3b, v42
	v_mul_f32_e32 v35, v35, v37
	v_exp_f32_e32 v36, v36
	v_mul_f32_e32 v37, 0xbfb8aa3b, v43
	v_exp_f32_e32 v37, v37
	v_cvt_pk_bf16_f32 v34, v34, v35
	v_add_f32_e32 v35, 1.0, v36
	v_rcp_f32_e32 v35, v35
	v_add_f32_e32 v36, 1.0, v37
	v_rcp_f32_e32 v36, v36
	v_mul_f32_e32 v37, v42, v48
	v_mul_f32_e32 v35, v37, v35
	v_mul_f32_e32 v37, v43, v49
	v_mul_f32_e32 v36, v37, v36
	v_cvt_pk_bf16_f32 v35, v35, v36
	v_mad_i64_i32 v[36:37], s[22:23], v70, s68, v[112:113]
	v_lshl_add_u64 v[36:37], v[36:37], 0, v[114:115]
	v_pk_mul_f32 v[28:29], v[28:29], v[76:77] op_sel_hi:[1,0]
	global_store_dwordx4 v[36:37], v[32:35], off sc1
	v_pk_mul_f32 v[20:21], v[20:21], v[76:77] op_sel_hi:[1,0]
	v_pk_mul_f32 v[30:31], v[30:31], v[76:77] op_sel_hi:[1,0]
	v_pk_mul_f32 v[32:33], v[18:19], v[76:77] op_sel_hi:[1,0]
	v_mul_f32_e32 v18, 0xbfb8aa3b, v28
	v_exp_f32_e32 v34, v18
	v_mul_f32_e32 v18, 0xbfb8aa3b, v29
	v_exp_f32_e32 v35, v18
	v_pk_mul_f32 v[18:19], v[16:17], v[76:77] op_sel_hi:[1,0]
	v_add_f32_e32 v16, 1.0, v34
	v_rcp_f32_e32 v16, v16
	v_add_f32_e32 v17, 1.0, v35
	v_rcp_f32_e32 v17, v17
	v_mul_f32_e32 v20, v28, v20
	v_mul_f32_e32 v16, v20, v16
	v_mul_f32_e32 v20, v29, v21
	v_mul_f32_e32 v17, v20, v17
	v_mul_f32_e32 v20, 0xbfb8aa3b, v30
	v_exp_f32_e32 v20, v20
	v_mul_f32_e32 v21, 0xbfb8aa3b, v31
	v_exp_f32_e32 v21, v21
	v_cvt_pk_bf16_f32 v16, v16, v17
	v_add_f32_e32 v17, 1.0, v20
	v_rcp_f32_e32 v17, v17
	v_add_f32_e32 v20, 1.0, v21
	v_rcp_f32_e32 v20, v20
	v_pk_mul_f32 v[22:23], v[22:23], v[76:77] op_sel_hi:[1,0]
	v_pk_mul_f32 v[24:25], v[24:25], v[76:77] op_sel_hi:[1,0]
	v_mul_f32_e32 v21, v30, v22
	v_mul_f32_e32 v17, v21, v17
	v_mul_f32_e32 v21, v31, v23
	v_mul_f32_e32 v20, v21, v20
	v_mul_f32_e32 v21, 0xbfb8aa3b, v24
	v_exp_f32_e32 v21, v21
	v_mul_f32_e32 v22, 0xbfb8aa3b, v25
	v_exp_f32_e32 v22, v22
	v_cvt_pk_bf16_f32 v17, v17, v20
	v_add_f32_e32 v20, 1.0, v21
	v_rcp_f32_e32 v20, v20
	v_add_f32_e32 v21, 1.0, v22
	v_rcp_f32_e32 v21, v21
	v_pk_mul_f32 v[26:27], v[26:27], v[76:77] op_sel_hi:[1,0]
	v_mul_f32_e32 v18, v24, v18
	v_mul_f32_e32 v18, v18, v20
	v_mul_f32_e32 v19, v25, v19
	v_mul_f32_e32 v20, 0xbfb8aa3b, v26
	v_mul_f32_e32 v19, v19, v21
	v_exp_f32_e32 v20, v20
	v_mul_f32_e32 v21, 0xbfb8aa3b, v27
	v_exp_f32_e32 v21, v21
	v_cvt_pk_bf16_f32 v18, v18, v19
	v_add_f32_e32 v19, 1.0, v20
	v_rcp_f32_e32 v19, v19
	v_add_f32_e32 v20, 1.0, v21
	v_rcp_f32_e32 v20, v20
	v_mul_f32_e32 v21, v26, v32
	v_mul_f32_e32 v19, v21, v19
	v_mul_f32_e32 v21, v27, v33
	v_mul_f32_e32 v20, v21, v20
	v_cvt_pk_bf16_f32 v19, v19, v20
	v_mad_i64_i32 v[20:21], s[22:23], v66, s68, v[112:113]
	v_lshl_add_u64 v[20:21], v[20:21], 0, v[114:115]
	v_pk_mul_f32 v[12:13], v[12:13], v[68:69] op_sel_hi:[1,0]
	global_store_dwordx4 v[20:21], v[16:19], off sc1
	v_pk_mul_f32 v[4:5], v[4:5], v[68:69] op_sel_hi:[1,0]
	v_pk_mul_f32 v[14:15], v[14:15], v[68:69] op_sel_hi:[1,0]
	v_pk_mul_f32 v[16:17], v[2:3], v[68:69] op_sel_hi:[1,0]
	v_mul_f32_e32 v2, 0xbfb8aa3b, v12
	v_exp_f32_e32 v18, v2
	v_mul_f32_e32 v2, 0xbfb8aa3b, v13
	v_exp_f32_e32 v19, v2
	v_pk_mul_f32 v[2:3], v[0:1], v[68:69] op_sel_hi:[1,0]
	v_add_f32_e32 v0, 1.0, v18
	v_rcp_f32_e32 v0, v0
	v_add_f32_e32 v1, 1.0, v19
	v_rcp_f32_e32 v1, v1
	v_mul_f32_e32 v4, v12, v4
	v_mul_f32_e32 v0, v4, v0
	v_mul_f32_e32 v4, v13, v5
	v_mul_f32_e32 v1, v4, v1
	v_mul_f32_e32 v4, 0xbfb8aa3b, v14
	v_exp_f32_e32 v4, v4
	v_mul_f32_e32 v5, 0xbfb8aa3b, v15
	v_exp_f32_e32 v5, v5
	v_cvt_pk_bf16_f32 v0, v0, v1
	v_add_f32_e32 v1, 1.0, v4
	v_rcp_f32_e32 v1, v1
	v_add_f32_e32 v4, 1.0, v5
	v_rcp_f32_e32 v4, v4
	v_pk_mul_f32 v[6:7], v[6:7], v[68:69] op_sel_hi:[1,0]
	v_pk_mul_f32 v[8:9], v[8:9], v[68:69] op_sel_hi:[1,0]
	v_mul_f32_e32 v5, v14, v6
	v_mul_f32_e32 v1, v5, v1
	v_mul_f32_e32 v5, v15, v7
	v_mul_f32_e32 v4, v5, v4
	v_mul_f32_e32 v5, 0xbfb8aa3b, v8
	v_exp_f32_e32 v5, v5
	v_mul_f32_e32 v6, 0xbfb8aa3b, v9
	v_exp_f32_e32 v6, v6
	v_cvt_pk_bf16_f32 v1, v1, v4
	v_add_f32_e32 v4, 1.0, v5
	v_rcp_f32_e32 v4, v4
	v_add_f32_e32 v5, 1.0, v6
	v_rcp_f32_e32 v5, v5
	v_pk_mul_f32 v[10:11], v[10:11], v[68:69] op_sel_hi:[1,0]
	v_mul_f32_e32 v2, v8, v2
	v_mul_f32_e32 v2, v2, v4
	v_mul_f32_e32 v3, v9, v3
	v_mul_f32_e32 v4, 0xbfb8aa3b, v10
	v_mul_f32_e32 v3, v3, v5
	v_exp_f32_e32 v4, v4
	v_mul_f32_e32 v5, 0xbfb8aa3b, v11
	v_exp_f32_e32 v5, v5
	v_cvt_pk_bf16_f32 v2, v2, v3
	v_add_f32_e32 v3, 1.0, v4
	v_rcp_f32_e32 v3, v3
	v_add_f32_e32 v4, 1.0, v5
	v_rcp_f32_e32 v4, v4
	v_mul_f32_e32 v5, v10, v16
	v_mul_f32_e32 v3, v5, v3
	v_mul_f32_e32 v5, v11, v17
	v_mul_f32_e32 v4, v5, v4
	v_cvt_pk_bf16_f32 v3, v3, v4
	v_mad_i64_i32 v[4:5], s[22:23], v64, s68, v[112:113]
	v_lshl_add_u64 v[4:5], v[4:5], 0, v[114:115]
	global_store_dwordx4 v[4:5], v[0:3], off sc1
	s_cbranch_vccnz .LBB0_875
	s_andn2_b64 vcc, exec, s[4:5]
	s_cbranch_vccnz .LBB0_874
	s_barrier
	s_branch .LBB0_874

.LBB0_1360:
	s_lshl_b32 s13, s22, 8
	v_add_u32_e32 v138, s13, v141
	v_ashrrev_i32_e32 v139, 31, v138
	v_or_b32_e32 v154, 16, v138
	v_lshlrev_b64 v[152:153], 6, v[138:139]
	v_ashrrev_i32_e32 v155, 31, v154
	v_lshl_add_u64 v[152:153], v[128:129], 0, v[152:153]
	v_lshlrev_b64 v[154:155], 6, v[154:155]
	v_lshl_add_u64 v[158:159], v[128:129], 0, v[154:155]
	global_load_dwordx4 v[154:157], v[152:153], off
	global_load_dwordx4 v[168:171], v[158:159], off
	v_or_b32_e32 v152, 32, v138
	v_ashrrev_i32_e32 v153, 31, v152
	v_lshlrev_b64 v[152:153], 6, v[152:153]
	v_lshl_add_u64 v[152:153], v[128:129], 0, v[152:153]
	global_load_dwordx4 v[172:175], v[152:153], off
	v_or_b32_e32 v152, 48, v138
	v_ashrrev_i32_e32 v153, 31, v152
	v_lshlrev_b64 v[152:153], 6, v[152:153]
	v_lshl_add_u64 v[152:153], v[128:129], 0, v[152:153]
	global_load_dwordx4 v[176:179], v[152:153], off
	v_and_b32_e32 v140, 64, v150
	v_xor_b32_e32 v139, 16, v150
	v_add_u32_e32 v140, 64, v140
	v_xor_b32_e32 v152, 32, v150
	v_cmp_lt_i32_e32 vcc, v139, v140
	v_lshl_or_b32 v158, s71, 7, v146
	v_ashrrev_i32_e32 v159, 31, v158
	v_cndmask_b32_e32 v139, v150, v139, vcc
	v_cmp_lt_i32_e32 vcc, v152, v140
	s_waitcnt vmcnt(0)
	v_mov_b32_e32 v180, v155
	v_mov_b32_e32 v181, v156
	v_mov_b32_e32 v155, v157
	v_cndmask_b32_e32 v140, v150, v152, vcc
	v_pk_add_f32 v[154:155], v[180:181], v[154:155]
	v_lshlrev_b32_e32 v152, 2, v139
	v_lshlrev_b32_e32 v139, 2, v140
	v_mov_b32_e32 v156, v169
	v_mov_b32_e32 v157, v170
	v_mov_b32_e32 v169, v171
	v_add_f32_e32 v140, v154, v155
	v_mov_b32_e32 v170, v173
	v_mov_b32_e32 v171, v174
	v_mov_b32_e32 v173, v175
	v_pk_add_f32 v[154:155], v[156:157], v[168:169]
	ds_bpermute_b32 v153, v152, v140
	v_mov_b32_e32 v174, v177
	v_mov_b32_e32 v175, v178
	v_mov_b32_e32 v177, v179
	v_pk_add_f32 v[156:157], v[170:171], v[172:173]
	v_add_f32_e32 v154, v154, v155
	v_pk_add_f32 v[168:169], v[174:175], v[176:177]
	v_add_f32_e32 v155, v156, v157
	ds_bpermute_b32 v157, v152, v154
	v_add_f32_e32 v156, v168, v169
	ds_bpermute_b32 v168, v152, v155
	ds_bpermute_b32 v169, v152, v156
	s_waitcnt lgkmcnt(3)
	v_add_f32_e32 v140, v140, v153
	ds_bpermute_b32 v153, v139, v140
	s_waitcnt lgkmcnt(3)
	v_add_f32_e32 v154, v154, v157
	ds_bpermute_b32 v157, v139, v154
	s_waitcnt lgkmcnt(3)
	v_add_f32_e32 v155, v155, v168
	s_waitcnt lgkmcnt(2)
	v_add_f32_e32 v156, v156, v169
	ds_bpermute_b32 v168, v139, v155
	ds_bpermute_b32 v169, v139, v156
	s_waitcnt lgkmcnt(3)
	v_add_f32_e32 v140, v140, v153
	v_fmamk_f32 v140, v140, 0x3a800000, v151
	s_waitcnt lgkmcnt(2)
	v_add_f32_e32 v153, v154, v157
	v_rsq_f32_e32 v154, v140
	s_waitcnt lgkmcnt(1)
	v_add_f32_e32 v155, v155, v168
	s_waitcnt lgkmcnt(0)
	v_add_f32_e32 v156, v156, v169
	v_fmamk_f32 v140, v153, 0x3a800000, v151
	v_fmamk_f32 v153, v155, 0x3a800000, v151
	v_fmamk_f32 v155, v156, 0x3a800000, v151
	v_pk_mul_f32 v[126:127], v[126:127], v[154:155] op_sel_hi:[1,0]
	v_pk_mul_f32 v[124:125], v[124:125], v[154:155] op_sel_hi:[1,0]
	v_pk_mul_f32 v[118:119], v[118:119], v[154:155] op_sel_hi:[1,0]
	v_pk_mul_f32 v[116:117], v[116:117], v[154:155] op_sel_hi:[1,0]
	v_mul_f32_e32 v118, v126, v118
	v_mul_f32_e32 v116, v124, v116
	v_mul_f32_e32 v124, 0xbfb8aa3b, v124
	v_mul_f32_e32 v117, v125, v117
	v_mul_f32_e32 v125, 0xbfb8aa3b, v125
	v_mul_f32_e32 v126, 0xbfb8aa3b, v126
	v_mul_f32_e32 v119, v127, v119
	v_mul_f32_e32 v127, 0xbfb8aa3b, v127
	v_exp_f32_e32 v124, v124
	v_exp_f32_e32 v125, v125
	v_exp_f32_e32 v126, v126
	v_exp_f32_e32 v127, v127
	v_pk_mul_f32 v[120:121], v[120:121], v[154:155] op_sel_hi:[1,0]
	v_pk_mul_f32 v[122:123], v[122:123], v[154:155] op_sel_hi:[1,0]
	v_pk_mul_f32 v[114:115], v[114:115], v[154:155] op_sel_hi:[1,0]
	v_pk_mul_f32 v[112:113], v[112:113], v[154:155] op_sel_hi:[1,0]
	v_mul_f32_e32 v154, 0xbfb8aa3b, v121
	v_add_f32_e32 v124, 1.0, v124
	v_add_f32_e32 v125, 1.0, v125
	v_add_f32_e32 v126, 1.0, v126
	v_exp_f32_e32 v154, v154
	v_add_f32_e32 v127, 1.0, v127
	v_rcp_f32_e32 v124, v124
	v_rcp_f32_e32 v125, v125
	v_rcp_f32_e32 v126, v126
	v_rcp_f32_e32 v127, v127
	v_rsq_f32_e32 v168, v153
	v_mul_f32_e32 v153, 0xbfb8aa3b, v120
	v_exp_f32_e32 v153, v153
	v_add_f32_e32 v154, 1.0, v154
	v_mul_f32_e32 v116, v116, v124
	v_mul_f32_e32 v117, v117, v125
	v_mul_f32_e32 v118, v118, v126
	v_mul_f32_e32 v119, v119, v127
	v_cvt_pk_bf16_f32 v116, v116, v117
	v_cvt_pk_bf16_f32 v117, v118, v119
	v_rcp_f32_e32 v118, v154
	v_add_f32_e32 v153, 1.0, v153
	v_mul_f32_e32 v113, v121, v113
	v_rcp_f32_e32 v153, v153
	v_mul_f32_e32 v113, v113, v118
	v_mul_f32_e32 v118, 0xbfb8aa3b, v122
	v_exp_f32_e32 v119, v118
	v_mul_f32_e32 v118, 0xbfb8aa3b, v123
	v_mul_f32_e32 v112, v120, v112
	v_exp_f32_e32 v120, v118
	v_mul_f32_e32 v112, v112, v153
	v_cvt_pk_bf16_f32 v118, v112, v113
	v_add_f32_e32 v112, 1.0, v119
	v_rcp_f32_e32 v112, v112
	v_add_f32_e32 v113, 1.0, v120
	v_rcp_f32_e32 v113, v113
	v_mul_f32_e32 v114, v122, v114
	v_rsq_f32_e32 v156, v140
	v_mul_f32_e32 v112, v114, v112
	v_mul_f32_e32 v114, v123, v115
	v_mul_f32_e32 v113, v114, v113
	v_cvt_pk_bf16_f32 v119, v112, v113
	v_mov_b64_e32 v[112:113], s[36:37]
	v_mad_i64_i32 v[120:121], s[24:25], v138, s70, v[112:113]
	v_lshlrev_b64 v[114:115], 1, v[158:159]
	v_lshl_add_u64 v[120:121], v[120:121], 0, v[114:115]
	v_pk_mul_f32 v[108:109], v[108:109], v[156:157] op_sel_hi:[1,0]
	global_store_dwordx4 v[120:121], v[116:119], off sc1
	v_pk_mul_f32 v[100:101], v[100:101], v[156:157] op_sel_hi:[1,0]
	v_pk_mul_f32 v[110:111], v[110:111], v[156:157] op_sel_hi:[1,0]
	v_pk_mul_f32 v[116:117], v[98:99], v[156:157] op_sel_hi:[1,0]
	v_mul_f32_e32 v98, 0xbfb8aa3b, v108
	v_exp_f32_e32 v119, v98
	v_mul_f32_e32 v98, 0xbfb8aa3b, v109
	v_exp_f32_e32 v120, v98
	v_pk_mul_f32 v[98:99], v[96:97], v[156:157] op_sel_hi:[1,0]
	v_add_f32_e32 v96, 1.0, v119
	v_rcp_f32_e32 v96, v96
	v_add_f32_e32 v97, 1.0, v120
	v_rcp_f32_e32 v97, v97
	v_mul_f32_e32 v100, v108, v100
	v_mul_f32_e32 v96, v100, v96
	v_mul_f32_e32 v100, v109, v101
	v_mul_f32_e32 v97, v100, v97
	v_mul_f32_e32 v100, 0xbfb8aa3b, v110
	v_exp_f32_e32 v100, v100
	v_mul_f32_e32 v101, 0xbfb8aa3b, v111
	v_exp_f32_e32 v101, v101
	v_cvt_pk_bf16_f32 v96, v96, v97
	v_add_f32_e32 v97, 1.0, v100
	v_rcp_f32_e32 v97, v97
	v_add_f32_e32 v100, 1.0, v101
	v_rcp_f32_e32 v100, v100
	v_pk_mul_f32 v[102:103], v[102:103], v[156:157] op_sel_hi:[1,0]
	v_pk_mul_f32 v[104:105], v[104:105], v[156:157] op_sel_hi:[1,0]
	v_mul_f32_e32 v101, v110, v102
	v_mul_f32_e32 v97, v101, v97
	v_mul_f32_e32 v101, v111, v103
	v_mul_f32_e32 v100, v101, v100
	v_mul_f32_e32 v101, 0xbfb8aa3b, v104
	v_exp_f32_e32 v101, v101
	v_mul_f32_e32 v102, 0xbfb8aa3b, v105
	v_exp_f32_e32 v102, v102
	v_cvt_pk_bf16_f32 v97, v97, v100
	v_add_f32_e32 v100, 1.0, v101
	v_rcp_f32_e32 v100, v100
	v_add_f32_e32 v101, 1.0, v102
	v_rcp_f32_e32 v101, v101
	v_pk_mul_f32 v[106:107], v[106:107], v[156:157] op_sel_hi:[1,0]
	v_mul_f32_e32 v98, v104, v98
	v_mul_f32_e32 v98, v98, v100
	v_mul_f32_e32 v99, v105, v99
	v_mul_f32_e32 v100, 0xbfb8aa3b, v106
	v_mul_f32_e32 v99, v99, v101
	v_exp_f32_e32 v100, v100
	v_mul_f32_e32 v101, 0xbfb8aa3b, v107
	v_exp_f32_e32 v101, v101
	v_cvt_pk_bf16_f32 v98, v98, v99
	v_add_f32_e32 v99, 1.0, v100
	v_rcp_f32_e32 v99, v99
	v_add_f32_e32 v100, 1.0, v101
	v_rcp_f32_e32 v100, v100
	v_mul_f32_e32 v101, v106, v116
	v_mul_f32_e32 v99, v101, v99
	v_mul_f32_e32 v101, v107, v117
	v_add_u32_e32 v118, s13, v143
	v_mul_f32_e32 v100, v101, v100
	v_cvt_pk_bf16_f32 v99, v99, v100
	v_mad_i64_i32 v[100:101], s[24:25], v118, s70, v[112:113]
	v_lshl_add_u64 v[100:101], v[100:101], 0, v[114:115]
	v_pk_mul_f32 v[92:93], v[92:93], v[168:169] op_sel_hi:[1,0]
	global_store_dwordx4 v[100:101], v[96:99], off sc1
	v_pk_mul_f32 v[84:85], v[84:85], v[168:169] op_sel_hi:[1,0]
	v_pk_mul_f32 v[94:95], v[94:95], v[168:169] op_sel_hi:[1,0]
	v_pk_mul_f32 v[96:97], v[82:83], v[168:169] op_sel_hi:[1,0]
	v_mul_f32_e32 v82, 0xbfb8aa3b, v92
	v_exp_f32_e32 v99, v82
	v_mul_f32_e32 v82, 0xbfb8aa3b, v93
	v_exp_f32_e32 v100, v82
	v_pk_mul_f32 v[82:83], v[80:81], v[168:169] op_sel_hi:[1,0]
	v_add_f32_e32 v80, 1.0, v99
	v_rcp_f32_e32 v80, v80
	v_add_f32_e32 v81, 1.0, v100
	v_rcp_f32_e32 v81, v81
	v_mul_f32_e32 v84, v92, v84
	v_mul_f32_e32 v80, v84, v80
	v_mul_f32_e32 v84, v93, v85
	v_mul_f32_e32 v81, v84, v81
	v_mul_f32_e32 v84, 0xbfb8aa3b, v94
	v_exp_f32_e32 v84, v84
	v_mul_f32_e32 v85, 0xbfb8aa3b, v95
	v_exp_f32_e32 v85, v85
	v_cvt_pk_bf16_f32 v80, v80, v81
	v_add_f32_e32 v81, 1.0, v84
	v_rcp_f32_e32 v81, v81
	v_add_f32_e32 v84, 1.0, v85
	v_rcp_f32_e32 v84, v84
	v_pk_mul_f32 v[86:87], v[86:87], v[168:169] op_sel_hi:[1,0]
	v_pk_mul_f32 v[88:89], v[88:89], v[168:169] op_sel_hi:[1,0]
	v_mul_f32_e32 v85, v94, v86
	v_mul_f32_e32 v81, v85, v81
	v_mul_f32_e32 v85, v95, v87
	v_mul_f32_e32 v84, v85, v84
	v_mul_f32_e32 v85, 0xbfb8aa3b, v88
	v_exp_f32_e32 v85, v85
	v_mul_f32_e32 v86, 0xbfb8aa3b, v89
	v_exp_f32_e32 v86, v86
	v_cvt_pk_bf16_f32 v81, v81, v84
	v_add_f32_e32 v84, 1.0, v85
	v_rcp_f32_e32 v84, v84
	v_add_f32_e32 v85, 1.0, v86
	v_rcp_f32_e32 v85, v85
	v_pk_mul_f32 v[90:91], v[90:91], v[168:169] op_sel_hi:[1,0]
	v_mul_f32_e32 v82, v88, v82
	v_mul_f32_e32 v82, v82, v84
	v_mul_f32_e32 v83, v89, v83
	v_mul_f32_e32 v84, 0xbfb8aa3b, v90
	v_mul_f32_e32 v83, v83, v85
	v_exp_f32_e32 v84, v84
	v_mul_f32_e32 v85, 0xbfb8aa3b, v91
	v_exp_f32_e32 v85, v85
	v_cvt_pk_bf16_f32 v82, v82, v83
	v_add_f32_e32 v83, 1.0, v84
	v_rcp_f32_e32 v83, v83
	v_add_f32_e32 v84, 1.0, v85
	v_rcp_f32_e32 v84, v84
	v_rsq_f32_e32 v140, v155
	v_mul_f32_e32 v85, v90, v96
	v_mul_f32_e32 v83, v85, v83
	v_mul_f32_e32 v85, v91, v97
	v_add_u32_e32 v98, s13, v144
	v_mul_f32_e32 v84, v85, v84
	v_cvt_pk_bf16_f32 v83, v83, v84
	v_mad_i64_i32 v[84:85], s[24:25], v98, s70, v[112:113]
	v_lshl_add_u64 v[84:85], v[84:85], 0, v[114:115]
	v_pk_mul_f32 v[76:77], v[76:77], v[140:141] op_sel_hi:[1,0]
	global_store_dwordx4 v[84:85], v[80:83], off sc1
	v_pk_mul_f32 v[68:69], v[68:69], v[140:141] op_sel_hi:[1,0]
	v_pk_mul_f32 v[78:79], v[78:79], v[140:141] op_sel_hi:[1,0]
	v_pk_mul_f32 v[80:81], v[66:67], v[140:141] op_sel_hi:[1,0]
	v_mul_f32_e32 v66, 0xbfb8aa3b, v76
	v_exp_f32_e32 v83, v66
	v_mul_f32_e32 v66, 0xbfb8aa3b, v77
	v_exp_f32_e32 v84, v66
	v_pk_mul_f32 v[66:67], v[64:65], v[140:141] op_sel_hi:[1,0]
	v_add_f32_e32 v64, 1.0, v83
	v_rcp_f32_e32 v64, v64
	v_add_f32_e32 v65, 1.0, v84
	v_rcp_f32_e32 v65, v65
	v_mul_f32_e32 v68, v76, v68
	v_mul_f32_e32 v64, v68, v64
	v_mul_f32_e32 v68, v77, v69
	v_mul_f32_e32 v65, v68, v65
	v_mul_f32_e32 v68, 0xbfb8aa3b, v78
	v_exp_f32_e32 v68, v68
	v_mul_f32_e32 v69, 0xbfb8aa3b, v79
	v_exp_f32_e32 v69, v69
	v_cvt_pk_bf16_f32 v64, v64, v65
	v_add_f32_e32 v65, 1.0, v68
	v_rcp_f32_e32 v65, v65
	v_add_f32_e32 v68, 1.0, v69
	v_rcp_f32_e32 v68, v68
	v_pk_mul_f32 v[70:71], v[70:71], v[140:141] op_sel_hi:[1,0]
	v_pk_mul_f32 v[72:73], v[72:73], v[140:141] op_sel_hi:[1,0]
	v_mul_f32_e32 v69, v78, v70
	v_mul_f32_e32 v65, v69, v65
	v_mul_f32_e32 v69, v79, v71
	v_mul_f32_e32 v68, v69, v68
	v_mul_f32_e32 v69, 0xbfb8aa3b, v72
	v_exp_f32_e32 v69, v69
	v_mul_f32_e32 v70, 0xbfb8aa3b, v73
	v_exp_f32_e32 v70, v70
	v_cvt_pk_bf16_f32 v65, v65, v68
	v_add_f32_e32 v68, 1.0, v69
	v_rcp_f32_e32 v68, v68
	v_add_f32_e32 v69, 1.0, v70
	v_rcp_f32_e32 v69, v69
	v_pk_mul_f32 v[74:75], v[74:75], v[140:141] op_sel_hi:[1,0]
	v_mul_f32_e32 v66, v72, v66
	v_mul_f32_e32 v66, v66, v68
	v_mul_f32_e32 v67, v73, v67
	v_mul_f32_e32 v68, 0xbfb8aa3b, v74
	v_mul_f32_e32 v67, v67, v69
	v_exp_f32_e32 v68, v68
	v_mul_f32_e32 v69, 0xbfb8aa3b, v75
	v_exp_f32_e32 v69, v69
	v_cvt_pk_bf16_f32 v66, v66, v67
	v_add_f32_e32 v67, 1.0, v68
	v_rcp_f32_e32 v67, v67
	v_add_f32_e32 v68, 1.0, v69
	v_rcp_f32_e32 v68, v68
	v_mul_f32_e32 v69, v74, v80
	v_mul_f32_e32 v67, v69, v67
	v_mul_f32_e32 v69, v75, v81
	v_add_u32_e32 v82, s13, v145
	v_mul_f32_e32 v68, v69, v68
	v_cvt_pk_bf16_f32 v67, v67, v68
	v_mad_i64_i32 v[68:69], s[24:25], v82, s70, v[112:113]
	v_add_u32_e32 v88, 0x80, v138
	v_lshl_add_u64 v[68:69], v[68:69], 0, v[114:115]
	v_ashrrev_i32_e32 v89, 31, v88
	global_store_dwordx4 v[68:69], v[64:67], off sc1
	v_add_u32_e32 v70, 0x90, v138
	v_ashrrev_i32_e32 v71, 31, v70
	v_lshlrev_b64 v[64:65], 6, v[88:89]
	v_lshl_add_u64 v[64:65], v[128:129], 0, v[64:65]
	global_load_dwordx4 v[72:75], v[64:65], off
	v_lshlrev_b64 v[64:65], 6, v[70:71]
	v_lshl_add_u64 v[64:65], v[128:129], 0, v[64:65]
	global_load_dwordx4 v[76:79], v[64:65], off
	v_add_u32_e32 v66, 0xa0, v138
	v_ashrrev_i32_e32 v67, 31, v66
	v_lshlrev_b64 v[64:65], 6, v[66:67]
	v_lshl_add_u64 v[64:65], v[128:129], 0, v[64:65]
	global_load_dwordx4 v[80:83], v[64:65], off
	v_add_u32_e32 v64, 0xb0, v138
	v_ashrrev_i32_e32 v65, 31, v64
	v_lshlrev_b64 v[68:69], 6, v[64:65]
	v_lshl_add_u64 v[68:69], v[128:129], 0, v[68:69]
	global_load_dwordx4 v[84:87], v[68:69], off
	s_andn2_b64 vcc, exec, s[0:1]
	s_mov_b64 s[0:1], -1
	s_waitcnt vmcnt(3)
	v_mov_b32_e32 v68, v73
	v_mov_b32_e32 v69, v74
	v_mov_b32_e32 v73, v75
	v_pk_add_f32 v[68:69], v[68:69], v[72:73]
	s_nop 0
	v_add_f32_e32 v65, v68, v69
	ds_bpermute_b32 v67, v152, v65
	s_waitcnt vmcnt(2)
	v_mov_b32_e32 v68, v77
	v_mov_b32_e32 v69, v78
	v_mov_b32_e32 v77, v79
	v_pk_add_f32 v[68:69], v[68:69], v[76:77]
	s_waitcnt lgkmcnt(0)
	v_add_f32_e32 v65, v65, v67
	ds_bpermute_b32 v67, v139, v65
	v_add_f32_e32 v68, v68, v69
	ds_bpermute_b32 v69, v152, v68
	s_waitcnt lgkmcnt(1)
	v_add_f32_e32 v65, v65, v67
	v_fmamk_f32 v65, v65, 0x3a800000, v151
	v_rsq_f32_e32 v72, v65
	s_waitcnt lgkmcnt(0)
	v_add_f32_e32 v65, v68, v69
	s_waitcnt vmcnt(1)
	v_mov_b32_e32 v68, v81
	v_mov_b32_e32 v69, v82
	v_mov_b32_e32 v81, v83
	v_pk_add_f32 v[68:69], v[68:69], v[80:81]
	ds_bpermute_b32 v67, v139, v65
	v_add_f32_e32 v71, v68, v69
	s_waitcnt vmcnt(0)
	v_mov_b32_e32 v68, v85
	v_mov_b32_e32 v69, v86
	v_mov_b32_e32 v85, v87
	ds_bpermute_b32 v73, v152, v71
	v_pk_add_f32 v[68:69], v[68:69], v[84:85]
	s_waitcnt lgkmcnt(1)
	v_add_f32_e32 v65, v65, v67
	v_add_f32_e32 v68, v68, v69
	ds_bpermute_b32 v69, v152, v68
	s_waitcnt lgkmcnt(1)
	v_add_f32_e32 v67, v71, v73
	ds_bpermute_b32 v71, v139, v67
	v_fmamk_f32 v65, v65, 0x3a800000, v151
	v_rsq_f32_e32 v74, v65
	s_waitcnt lgkmcnt(1)
	v_add_f32_e32 v68, v68, v69
	ds_bpermute_b32 v69, v139, v68
	s_waitcnt lgkmcnt(1)
	v_add_f32_e32 v65, v67, v71
	v_fmamk_f32 v65, v65, 0x3a800000, v151
	v_rsq_f32_e32 v76, v65
	v_pk_mul_f32 v[60:61], v[60:61], v[72:73] op_sel_hi:[1,0]
	s_waitcnt lgkmcnt(0)
	v_add_f32_e32 v65, v68, v69
	v_fmamk_f32 v65, v65, 0x3a800000, v151
	v_pk_mul_f32 v[78:79], v[50:51], v[72:73] op_sel_hi:[1,0]
	v_mul_f32_e32 v50, 0xbfb8aa3b, v60
	v_rsq_f32_e32 v68, v65
	v_exp_f32_e32 v65, v50
	v_mul_f32_e32 v50, 0xbfb8aa3b, v61
	v_exp_f32_e32 v67, v50
	v_pk_mul_f32 v[50:51], v[48:49], v[72:73] op_sel_hi:[1,0]
	v_add_f32_e32 v48, 1.0, v65
	v_rcp_f32_e32 v48, v48
	v_add_f32_e32 v49, 1.0, v67
	v_rcp_f32_e32 v49, v49
	v_pk_mul_f32 v[52:53], v[52:53], v[72:73] op_sel_hi:[1,0]
	v_pk_mul_f32 v[62:63], v[62:63], v[72:73] op_sel_hi:[1,0]
	v_mul_f32_e32 v52, v60, v52
	v_mul_f32_e32 v48, v52, v48
	v_mul_f32_e32 v52, v61, v53
	v_mul_f32_e32 v49, v52, v49
	v_mul_f32_e32 v52, 0xbfb8aa3b, v62
	v_exp_f32_e32 v52, v52
	v_mul_f32_e32 v53, 0xbfb8aa3b, v63
	v_exp_f32_e32 v53, v53
	v_cvt_pk_bf16_f32 v48, v48, v49
	v_add_f32_e32 v49, 1.0, v52
	v_rcp_f32_e32 v49, v49
	v_add_f32_e32 v52, 1.0, v53
	v_rcp_f32_e32 v52, v52
	v_pk_mul_f32 v[54:55], v[54:55], v[72:73] op_sel_hi:[1,0]
	v_pk_mul_f32 v[56:57], v[56:57], v[72:73] op_sel_hi:[1,0]
	v_mul_f32_e32 v53, v62, v54
	v_mul_f32_e32 v49, v53, v49
	v_mul_f32_e32 v53, v63, v55
	v_mul_f32_e32 v52, v53, v52
	v_mul_f32_e32 v53, 0xbfb8aa3b, v56
	v_exp_f32_e32 v53, v53
	v_mul_f32_e32 v54, 0xbfb8aa3b, v57
	v_exp_f32_e32 v54, v54
	v_cvt_pk_bf16_f32 v49, v49, v52
	v_add_f32_e32 v52, 1.0, v53
	v_rcp_f32_e32 v52, v52
	v_add_f32_e32 v53, 1.0, v54
	v_rcp_f32_e32 v53, v53
	v_pk_mul_f32 v[58:59], v[58:59], v[72:73] op_sel_hi:[1,0]
	v_mul_f32_e32 v50, v56, v50
	v_mul_f32_e32 v50, v50, v52
	v_mul_f32_e32 v51, v57, v51
	v_mul_f32_e32 v52, 0xbfb8aa3b, v58
	v_mul_f32_e32 v51, v51, v53
	v_exp_f32_e32 v52, v52
	v_mul_f32_e32 v53, 0xbfb8aa3b, v59
	v_exp_f32_e32 v53, v53
	v_cvt_pk_bf16_f32 v50, v50, v51
	v_add_f32_e32 v51, 1.0, v52
	v_rcp_f32_e32 v51, v51
	v_add_f32_e32 v52, 1.0, v53
	v_rcp_f32_e32 v52, v52
	v_mul_f32_e32 v53, v58, v78
	v_mul_f32_e32 v51, v53, v51
	v_mul_f32_e32 v53, v59, v79
	v_mul_f32_e32 v52, v53, v52
	v_cvt_pk_bf16_f32 v51, v51, v52
	v_mad_i64_i32 v[52:53], s[24:25], v88, s70, v[112:113]
	v_lshl_add_u64 v[52:53], v[52:53], 0, v[114:115]
	v_pk_mul_f32 v[44:45], v[44:45], v[74:75] op_sel_hi:[1,0]
	global_store_dwordx4 v[52:53], v[48:51], off sc1
	v_pk_mul_f32 v[36:37], v[36:37], v[74:75] op_sel_hi:[1,0]
	v_pk_mul_f32 v[46:47], v[46:47], v[74:75] op_sel_hi:[1,0]
	v_pk_mul_f32 v[48:49], v[34:35], v[74:75] op_sel_hi:[1,0]
	v_mul_f32_e32 v34, 0xbfb8aa3b, v44
	v_exp_f32_e32 v50, v34
	v_mul_f32_e32 v34, 0xbfb8aa3b, v45
	v_exp_f32_e32 v51, v34
	v_pk_mul_f32 v[34:35], v[32:33], v[74:75] op_sel_hi:[1,0]
	v_add_f32_e32 v32, 1.0, v50
	v_rcp_f32_e32 v32, v32
	v_add_f32_e32 v33, 1.0, v51
	v_rcp_f32_e32 v33, v33
	v_mul_f32_e32 v36, v44, v36
	v_mul_f32_e32 v32, v36, v32
	v_mul_f32_e32 v36, v45, v37
	v_mul_f32_e32 v33, v36, v33
	v_mul_f32_e32 v36, 0xbfb8aa3b, v46
	v_exp_f32_e32 v36, v36
	v_mul_f32_e32 v37, 0xbfb8aa3b, v47
	v_exp_f32_e32 v37, v37
	v_cvt_pk_bf16_f32 v32, v32, v33
	v_add_f32_e32 v33, 1.0, v36
	v_rcp_f32_e32 v33, v33
	v_add_f32_e32 v36, 1.0, v37
	v_rcp_f32_e32 v36, v36
	v_pk_mul_f32 v[38:39], v[38:39], v[74:75] op_sel_hi:[1,0]
	v_pk_mul_f32 v[40:41], v[40:41], v[74:75] op_sel_hi:[1,0]
	v_mul_f32_e32 v37, v46, v38
	v_mul_f32_e32 v33, v37, v33
	v_mul_f32_e32 v37, v47, v39
	v_mul_f32_e32 v36, v37, v36
	v_mul_f32_e32 v37, 0xbfb8aa3b, v40
	v_exp_f32_e32 v37, v37
	v_mul_f32_e32 v38, 0xbfb8aa3b, v41
	v_exp_f32_e32 v38, v38
	v_cvt_pk_bf16_f32 v33, v33, v36
	v_add_f32_e32 v36, 1.0, v37
	v_rcp_f32_e32 v36, v36
	v_add_f32_e32 v37, 1.0, v38
	v_rcp_f32_e32 v37, v37
	v_pk_mul_f32 v[42:43], v[42:43], v[74:75] op_sel_hi:[1,0]
	v_mul_f32_e32 v34, v40, v34
	v_mul_f32_e32 v34, v34, v36
	v_mul_f32_e32 v35, v41, v35
	v_mul_f32_e32 v36, 0xbfb8aa3b, v42
	v_mul_f32_e32 v35, v35, v37
	v_exp_f32_e32 v36, v36
	v_mul_f32_e32 v37, 0xbfb8aa3b, v43
	v_exp_f32_e32 v37, v37
	v_cvt_pk_bf16_f32 v34, v34, v35
	v_add_f32_e32 v35, 1.0, v36
	v_rcp_f32_e32 v35, v35
	v_add_f32_e32 v36, 1.0, v37
	v_rcp_f32_e32 v36, v36
	v_mul_f32_e32 v37, v42, v48
	v_mul_f32_e32 v35, v37, v35
	v_mul_f32_e32 v37, v43, v49
	v_mul_f32_e32 v36, v37, v36
	v_cvt_pk_bf16_f32 v35, v35, v36
	v_mad_i64_i32 v[36:37], s[24:25], v70, s70, v[112:113]
	v_lshl_add_u64 v[36:37], v[36:37], 0, v[114:115]
	v_pk_mul_f32 v[28:29], v[28:29], v[76:77] op_sel_hi:[1,0]
	global_store_dwordx4 v[36:37], v[32:35], off sc1
	v_pk_mul_f32 v[20:21], v[20:21], v[76:77] op_sel_hi:[1,0]
	v_pk_mul_f32 v[30:31], v[30:31], v[76:77] op_sel_hi:[1,0]
	v_pk_mul_f32 v[32:33], v[18:19], v[76:77] op_sel_hi:[1,0]
	v_mul_f32_e32 v18, 0xbfb8aa3b, v28
	v_exp_f32_e32 v34, v18
	v_mul_f32_e32 v18, 0xbfb8aa3b, v29
	v_exp_f32_e32 v35, v18
	v_pk_mul_f32 v[18:19], v[16:17], v[76:77] op_sel_hi:[1,0]
	v_add_f32_e32 v16, 1.0, v34
	v_rcp_f32_e32 v16, v16
	v_add_f32_e32 v17, 1.0, v35
	v_rcp_f32_e32 v17, v17
	v_mul_f32_e32 v20, v28, v20
	v_mul_f32_e32 v16, v20, v16
	v_mul_f32_e32 v20, v29, v21
	v_mul_f32_e32 v17, v20, v17
	v_mul_f32_e32 v20, 0xbfb8aa3b, v30
	v_exp_f32_e32 v20, v20
	v_mul_f32_e32 v21, 0xbfb8aa3b, v31
	v_exp_f32_e32 v21, v21
	v_cvt_pk_bf16_f32 v16, v16, v17
	v_add_f32_e32 v17, 1.0, v20
	v_rcp_f32_e32 v17, v17
	v_add_f32_e32 v20, 1.0, v21
	v_rcp_f32_e32 v20, v20
	v_pk_mul_f32 v[22:23], v[22:23], v[76:77] op_sel_hi:[1,0]
	v_pk_mul_f32 v[24:25], v[24:25], v[76:77] op_sel_hi:[1,0]
	v_mul_f32_e32 v21, v30, v22
	v_mul_f32_e32 v17, v21, v17
	v_mul_f32_e32 v21, v31, v23
	v_mul_f32_e32 v20, v21, v20
	v_mul_f32_e32 v21, 0xbfb8aa3b, v24
	v_exp_f32_e32 v21, v21
	v_mul_f32_e32 v22, 0xbfb8aa3b, v25
	v_exp_f32_e32 v22, v22
	v_cvt_pk_bf16_f32 v17, v17, v20
	v_add_f32_e32 v20, 1.0, v21
	v_rcp_f32_e32 v20, v20
	v_add_f32_e32 v21, 1.0, v22
	v_rcp_f32_e32 v21, v21
	v_pk_mul_f32 v[26:27], v[26:27], v[76:77] op_sel_hi:[1,0]
	v_mul_f32_e32 v18, v24, v18
	v_mul_f32_e32 v18, v18, v20
	v_mul_f32_e32 v19, v25, v19
	v_mul_f32_e32 v20, 0xbfb8aa3b, v26
	v_mul_f32_e32 v19, v19, v21
	v_exp_f32_e32 v20, v20
	v_mul_f32_e32 v21, 0xbfb8aa3b, v27
	v_exp_f32_e32 v21, v21
	v_cvt_pk_bf16_f32 v18, v18, v19
	v_add_f32_e32 v19, 1.0, v20
	v_rcp_f32_e32 v19, v19
	v_add_f32_e32 v20, 1.0, v21
	v_rcp_f32_e32 v20, v20
	v_mul_f32_e32 v21, v26, v32
	v_mul_f32_e32 v19, v21, v19
	v_mul_f32_e32 v21, v27, v33
	v_mul_f32_e32 v20, v21, v20
	v_cvt_pk_bf16_f32 v19, v19, v20
	v_mad_i64_i32 v[20:21], s[24:25], v66, s70, v[112:113]
	v_lshl_add_u64 v[20:21], v[20:21], 0, v[114:115]
	v_pk_mul_f32 v[12:13], v[12:13], v[68:69] op_sel_hi:[1,0]
	global_store_dwordx4 v[20:21], v[16:19], off sc1
	v_pk_mul_f32 v[4:5], v[4:5], v[68:69] op_sel_hi:[1,0]
	v_pk_mul_f32 v[14:15], v[14:15], v[68:69] op_sel_hi:[1,0]
	v_pk_mul_f32 v[16:17], v[2:3], v[68:69] op_sel_hi:[1,0]
	v_mul_f32_e32 v2, 0xbfb8aa3b, v12
	v_exp_f32_e32 v18, v2
	v_mul_f32_e32 v2, 0xbfb8aa3b, v13
	v_exp_f32_e32 v19, v2
	v_pk_mul_f32 v[2:3], v[0:1], v[68:69] op_sel_hi:[1,0]
	v_add_f32_e32 v0, 1.0, v18
	v_rcp_f32_e32 v0, v0
	v_add_f32_e32 v1, 1.0, v19
	v_rcp_f32_e32 v1, v1
	v_mul_f32_e32 v4, v12, v4
	v_mul_f32_e32 v0, v4, v0
	v_mul_f32_e32 v4, v13, v5
	v_mul_f32_e32 v1, v4, v1
	v_mul_f32_e32 v4, 0xbfb8aa3b, v14
	v_exp_f32_e32 v4, v4
	v_mul_f32_e32 v5, 0xbfb8aa3b, v15
	v_exp_f32_e32 v5, v5
	v_cvt_pk_bf16_f32 v0, v0, v1
	v_add_f32_e32 v1, 1.0, v4
	v_rcp_f32_e32 v1, v1
	v_add_f32_e32 v4, 1.0, v5
	v_rcp_f32_e32 v4, v4
	v_pk_mul_f32 v[6:7], v[6:7], v[68:69] op_sel_hi:[1,0]
	v_pk_mul_f32 v[8:9], v[8:9], v[68:69] op_sel_hi:[1,0]
	v_mul_f32_e32 v5, v14, v6
	v_mul_f32_e32 v1, v5, v1
	v_mul_f32_e32 v5, v15, v7
	v_mul_f32_e32 v4, v5, v4
	v_mul_f32_e32 v5, 0xbfb8aa3b, v8
	v_exp_f32_e32 v5, v5
	v_mul_f32_e32 v6, 0xbfb8aa3b, v9
	v_exp_f32_e32 v6, v6
	v_cvt_pk_bf16_f32 v1, v1, v4
	v_add_f32_e32 v4, 1.0, v5
	v_rcp_f32_e32 v4, v4
	v_add_f32_e32 v5, 1.0, v6
	v_rcp_f32_e32 v5, v5
	v_pk_mul_f32 v[10:11], v[10:11], v[68:69] op_sel_hi:[1,0]
	v_mul_f32_e32 v2, v8, v2
	v_mul_f32_e32 v2, v2, v4
	v_mul_f32_e32 v3, v9, v3
	v_mul_f32_e32 v4, 0xbfb8aa3b, v10
	v_mul_f32_e32 v3, v3, v5
	v_exp_f32_e32 v4, v4
	v_mul_f32_e32 v5, 0xbfb8aa3b, v11
	v_exp_f32_e32 v5, v5
	v_cvt_pk_bf16_f32 v2, v2, v3
	v_add_f32_e32 v3, 1.0, v4
	v_rcp_f32_e32 v3, v3
	v_add_f32_e32 v4, 1.0, v5
	v_rcp_f32_e32 v4, v4
	v_mul_f32_e32 v5, v10, v16
	v_mul_f32_e32 v3, v5, v3
	v_mul_f32_e32 v5, v11, v17
	v_mul_f32_e32 v4, v5, v4
	v_cvt_pk_bf16_f32 v3, v3, v4
	v_mad_i64_i32 v[4:5], s[24:25], v64, s70, v[112:113]
	v_lshl_add_u64 v[4:5], v[4:5], 0, v[114:115]
	global_store_dwordx4 v[4:5], v[0:3], off sc1
	s_cbranch_vccnz .LBB0_1353
	s_andn2_b64 vcc, exec, s[2:3]
	s_cbranch_vccnz .LBB0_1352
	s_barrier
	s_branch .LBB0_1352

.LBB0_2126:
	s_lshl_b32 s11, s18, 8
	v_add_u32_e32 v146, s11, v149
	v_or_b32_e32 v162, 16, v146
	v_ashrrev_i32_e32 v147, 31, v146
	v_ashrrev_i32_e32 v163, 31, v162
	v_lshlrev_b64 v[160:161], 6, v[146:147]
	v_lshlrev_b64 v[162:163], 6, v[162:163]
	v_lshl_add_u64 v[160:161], v[136:137], 0, v[160:161]
	v_lshl_add_u64 v[166:167], v[136:137], 0, v[162:163]
	global_load_dwordx4 v[162:165], v[160:161], off
	s_nop 0
	global_load_dwordx4 v[166:169], v[166:167], off
	v_or_b32_e32 v160, 32, v146
	v_ashrrev_i32_e32 v161, 31, v160
	v_lshlrev_b64 v[160:161], 6, v[160:161]
	v_lshl_add_u64 v[160:161], v[136:137], 0, v[160:161]
	global_load_dwordx4 v[170:173], v[160:161], off
	v_or_b32_e32 v160, 48, v146
	v_ashrrev_i32_e32 v161, 31, v160
	v_lshlrev_b64 v[160:161], 6, v[160:161]
	v_lshl_add_u64 v[160:161], v[136:137], 0, v[160:161]
	global_load_dwordx4 v[174:177], v[160:161], off
	v_and_b32_e32 v148, 64, v158
	v_xor_b32_e32 v147, 16, v158
	v_add_u32_e32 v148, 64, v148
	v_xor_b32_e32 v160, 32, v158
	v_cmp_lt_i32_e32 vcc, v147, v148
	v_lshl_or_b32 v178, s49, 7, v154
	v_ashrrev_i32_e32 v179, 31, v178
	v_cndmask_b32_e32 v147, v158, v147, vcc
	v_cmp_lt_i32_e32 vcc, v160, v148
	s_waitcnt vmcnt(0)
	v_mov_b32_e32 v180, v163
	v_mov_b32_e32 v181, v164
	v_mov_b32_e32 v163, v165
	v_cndmask_b32_e32 v148, v158, v160, vcc
	v_pk_add_f32 v[162:163], v[180:181], v[162:163]
	v_lshlrev_b32_e32 v160, 2, v147
	v_lshlrev_b32_e32 v147, 2, v148
	v_mov_b32_e32 v164, v167
	v_mov_b32_e32 v165, v168
	v_mov_b32_e32 v167, v169
	v_add_f32_e32 v148, v162, v163
	v_mov_b32_e32 v168, v171
	v_mov_b32_e32 v169, v172
	v_mov_b32_e32 v171, v173
	v_pk_add_f32 v[162:163], v[164:165], v[166:167]
	ds_bpermute_b32 v161, v160, v148
	v_mov_b32_e32 v172, v175
	v_mov_b32_e32 v173, v176
	v_mov_b32_e32 v175, v177
	v_pk_add_f32 v[164:165], v[168:169], v[170:171]
	v_add_f32_e32 v162, v162, v163
	v_pk_add_f32 v[166:167], v[172:173], v[174:175]
	v_add_f32_e32 v163, v164, v165
	ds_bpermute_b32 v165, v160, v162
	v_add_f32_e32 v164, v166, v167
	ds_bpermute_b32 v166, v160, v163
	ds_bpermute_b32 v167, v160, v164
	s_waitcnt lgkmcnt(3)
	v_add_f32_e32 v148, v148, v161
	ds_bpermute_b32 v161, v147, v148
	s_waitcnt lgkmcnt(3)
	v_add_f32_e32 v162, v162, v165
	ds_bpermute_b32 v165, v147, v162
	s_waitcnt lgkmcnt(3)
	v_add_f32_e32 v163, v163, v166
	s_waitcnt lgkmcnt(2)
	v_add_f32_e32 v164, v164, v167
	ds_bpermute_b32 v166, v147, v163
	ds_bpermute_b32 v167, v147, v164
	s_waitcnt lgkmcnt(3)
	v_add_f32_e32 v148, v148, v161
	v_fmamk_f32 v148, v148, 0x3a800000, v159
	s_waitcnt lgkmcnt(2)
	v_add_f32_e32 v161, v162, v165
	v_rsq_f32_e32 v162, v148
	s_waitcnt lgkmcnt(1)
	v_add_f32_e32 v163, v163, v166
	s_waitcnt lgkmcnt(0)
	v_add_f32_e32 v164, v164, v167
	v_fmamk_f32 v148, v161, 0x3a800000, v159
	v_fmamk_f32 v161, v163, 0x3a800000, v159
	v_fmamk_f32 v163, v164, 0x3a800000, v159
	v_pk_mul_f32 v[126:127], v[126:127], v[162:163] op_sel_hi:[1,0]
	v_pk_mul_f32 v[124:125], v[124:125], v[162:163] op_sel_hi:[1,0]
	v_pk_mul_f32 v[118:119], v[118:119], v[162:163] op_sel_hi:[1,0]
	v_pk_mul_f32 v[116:117], v[116:117], v[162:163] op_sel_hi:[1,0]
	v_mul_f32_e32 v118, v126, v118
	v_mul_f32_e32 v116, v124, v116
	v_mul_f32_e32 v124, 0xbfb8aa3b, v124
	v_mul_f32_e32 v117, v125, v117
	v_mul_f32_e32 v125, 0xbfb8aa3b, v125
	v_mul_f32_e32 v126, 0xbfb8aa3b, v126
	v_mul_f32_e32 v119, v127, v119
	v_mul_f32_e32 v127, 0xbfb8aa3b, v127
	v_exp_f32_e32 v124, v124
	v_exp_f32_e32 v125, v125
	v_exp_f32_e32 v126, v126
	v_exp_f32_e32 v127, v127
	v_pk_mul_f32 v[120:121], v[120:121], v[162:163] op_sel_hi:[1,0]
	v_pk_mul_f32 v[122:123], v[122:123], v[162:163] op_sel_hi:[1,0]
	v_pk_mul_f32 v[114:115], v[114:115], v[162:163] op_sel_hi:[1,0]
	v_pk_mul_f32 v[112:113], v[112:113], v[162:163] op_sel_hi:[1,0]
	v_mul_f32_e32 v162, 0xbfb8aa3b, v121
	v_add_f32_e32 v124, 1.0, v124
	v_add_f32_e32 v125, 1.0, v125
	v_add_f32_e32 v126, 1.0, v126
	v_exp_f32_e32 v162, v162
	v_add_f32_e32 v127, 1.0, v127
	v_rcp_f32_e32 v124, v124
	v_rcp_f32_e32 v125, v125
	v_rcp_f32_e32 v126, v126
	v_rcp_f32_e32 v127, v127
	v_rsq_f32_e32 v166, v161
	v_mul_f32_e32 v161, 0xbfb8aa3b, v120
	v_exp_f32_e32 v161, v161
	v_add_f32_e32 v162, 1.0, v162
	v_mul_f32_e32 v116, v116, v124
	v_mul_f32_e32 v117, v117, v125
	v_mul_f32_e32 v118, v118, v126
	v_mul_f32_e32 v119, v119, v127
	v_cvt_pk_bf16_f32 v116, v116, v117
	v_cvt_pk_bf16_f32 v117, v118, v119
	v_rcp_f32_e32 v118, v162
	v_add_f32_e32 v161, 1.0, v161
	v_mul_f32_e32 v113, v121, v113
	v_rcp_f32_e32 v161, v161
	v_mul_f32_e32 v113, v113, v118
	v_mul_f32_e32 v118, 0xbfb8aa3b, v122
	v_exp_f32_e32 v119, v118
	v_mul_f32_e32 v118, 0xbfb8aa3b, v123
	v_mul_f32_e32 v112, v120, v112
	v_exp_f32_e32 v120, v118
	v_mul_f32_e32 v112, v112, v161
	v_cvt_pk_bf16_f32 v118, v112, v113
	v_add_f32_e32 v112, 1.0, v119
	v_rcp_f32_e32 v112, v112
	v_add_f32_e32 v113, 1.0, v120
	v_rcp_f32_e32 v113, v113
	v_mul_f32_e32 v114, v122, v114
	v_rsq_f32_e32 v164, v148
	v_mul_f32_e32 v112, v114, v112
	v_mul_f32_e32 v114, v123, v115
	v_mul_f32_e32 v113, v114, v113
	v_cvt_pk_bf16_f32 v119, v112, v113
	v_mov_b64_e32 v[112:113], s[36:37]
	v_mad_i64_i32 v[120:121], s[20:21], v146, s48, v[112:113]
	v_lshlrev_b64 v[114:115], 1, v[178:179]
	v_lshl_add_u64 v[120:121], v[120:121], 0, v[114:115]
	v_pk_mul_f32 v[108:109], v[108:109], v[164:165] op_sel_hi:[1,0]
	global_store_dwordx4 v[120:121], v[116:119], off sc1
	v_pk_mul_f32 v[100:101], v[100:101], v[164:165] op_sel_hi:[1,0]
	v_pk_mul_f32 v[110:111], v[110:111], v[164:165] op_sel_hi:[1,0]
	v_pk_mul_f32 v[116:117], v[98:99], v[164:165] op_sel_hi:[1,0]
	v_mul_f32_e32 v98, 0xbfb8aa3b, v108
	v_exp_f32_e32 v119, v98
	v_mul_f32_e32 v98, 0xbfb8aa3b, v109
	v_exp_f32_e32 v120, v98
	v_pk_mul_f32 v[98:99], v[96:97], v[164:165] op_sel_hi:[1,0]
	v_add_f32_e32 v96, 1.0, v119
	v_rcp_f32_e32 v96, v96
	v_add_f32_e32 v97, 1.0, v120
	v_rcp_f32_e32 v97, v97
	v_mul_f32_e32 v100, v108, v100
	v_mul_f32_e32 v96, v100, v96
	v_mul_f32_e32 v100, v109, v101
	v_mul_f32_e32 v97, v100, v97
	v_mul_f32_e32 v100, 0xbfb8aa3b, v110
	v_exp_f32_e32 v100, v100
	v_mul_f32_e32 v101, 0xbfb8aa3b, v111
	v_exp_f32_e32 v101, v101
	v_cvt_pk_bf16_f32 v96, v96, v97
	v_add_f32_e32 v97, 1.0, v100
	v_rcp_f32_e32 v97, v97
	v_add_f32_e32 v100, 1.0, v101
	v_rcp_f32_e32 v100, v100
	v_pk_mul_f32 v[102:103], v[102:103], v[164:165] op_sel_hi:[1,0]
	v_pk_mul_f32 v[104:105], v[104:105], v[164:165] op_sel_hi:[1,0]
	v_mul_f32_e32 v101, v110, v102
	v_mul_f32_e32 v97, v101, v97
	v_mul_f32_e32 v101, v111, v103
	v_mul_f32_e32 v100, v101, v100
	v_mul_f32_e32 v101, 0xbfb8aa3b, v104
	v_exp_f32_e32 v101, v101
	v_mul_f32_e32 v102, 0xbfb8aa3b, v105
	v_exp_f32_e32 v102, v102
	v_cvt_pk_bf16_f32 v97, v97, v100
	v_add_f32_e32 v100, 1.0, v101
	v_rcp_f32_e32 v100, v100
	v_add_f32_e32 v101, 1.0, v102
	v_rcp_f32_e32 v101, v101
	v_pk_mul_f32 v[106:107], v[106:107], v[164:165] op_sel_hi:[1,0]
	v_mul_f32_e32 v98, v104, v98
	v_mul_f32_e32 v98, v98, v100
	v_mul_f32_e32 v99, v105, v99
	v_mul_f32_e32 v100, 0xbfb8aa3b, v106
	v_mul_f32_e32 v99, v99, v101
	v_exp_f32_e32 v100, v100
	v_mul_f32_e32 v101, 0xbfb8aa3b, v107
	v_exp_f32_e32 v101, v101
	v_cvt_pk_bf16_f32 v98, v98, v99
	v_add_f32_e32 v99, 1.0, v100
	v_rcp_f32_e32 v99, v99
	v_add_f32_e32 v100, 1.0, v101
	v_rcp_f32_e32 v100, v100
	v_mul_f32_e32 v101, v106, v116
	v_mul_f32_e32 v99, v101, v99
	v_mul_f32_e32 v101, v107, v117
	v_add_u32_e32 v118, s11, v151
	v_mul_f32_e32 v100, v101, v100
	v_cvt_pk_bf16_f32 v99, v99, v100
	v_mad_i64_i32 v[100:101], s[20:21], v118, s48, v[112:113]
	v_lshl_add_u64 v[100:101], v[100:101], 0, v[114:115]
	v_pk_mul_f32 v[92:93], v[92:93], v[166:167] op_sel_hi:[1,0]
	global_store_dwordx4 v[100:101], v[96:99], off sc1
	v_pk_mul_f32 v[84:85], v[84:85], v[166:167] op_sel_hi:[1,0]
	v_pk_mul_f32 v[94:95], v[94:95], v[166:167] op_sel_hi:[1,0]
	v_pk_mul_f32 v[96:97], v[82:83], v[166:167] op_sel_hi:[1,0]
	v_mul_f32_e32 v82, 0xbfb8aa3b, v92
	v_exp_f32_e32 v99, v82
	v_mul_f32_e32 v82, 0xbfb8aa3b, v93
	v_exp_f32_e32 v100, v82
	v_pk_mul_f32 v[82:83], v[80:81], v[166:167] op_sel_hi:[1,0]
	v_add_f32_e32 v80, 1.0, v99
	v_rcp_f32_e32 v80, v80
	v_add_f32_e32 v81, 1.0, v100
	v_rcp_f32_e32 v81, v81
	v_mul_f32_e32 v84, v92, v84
	v_mul_f32_e32 v80, v84, v80
	v_mul_f32_e32 v84, v93, v85
	v_mul_f32_e32 v81, v84, v81
	v_mul_f32_e32 v84, 0xbfb8aa3b, v94
	v_exp_f32_e32 v84, v84
	v_mul_f32_e32 v85, 0xbfb8aa3b, v95
	v_exp_f32_e32 v85, v85
	v_cvt_pk_bf16_f32 v80, v80, v81
	v_add_f32_e32 v81, 1.0, v84
	v_rcp_f32_e32 v81, v81
	v_add_f32_e32 v84, 1.0, v85
	v_rcp_f32_e32 v84, v84
	v_pk_mul_f32 v[86:87], v[86:87], v[166:167] op_sel_hi:[1,0]
	v_pk_mul_f32 v[88:89], v[88:89], v[166:167] op_sel_hi:[1,0]
	v_mul_f32_e32 v85, v94, v86
	v_mul_f32_e32 v81, v85, v81
	v_mul_f32_e32 v85, v95, v87
	v_mul_f32_e32 v84, v85, v84
	v_mul_f32_e32 v85, 0xbfb8aa3b, v88
	v_exp_f32_e32 v85, v85
	v_mul_f32_e32 v86, 0xbfb8aa3b, v89
	v_exp_f32_e32 v86, v86
	v_cvt_pk_bf16_f32 v81, v81, v84
	v_add_f32_e32 v84, 1.0, v85
	v_rcp_f32_e32 v84, v84
	v_add_f32_e32 v85, 1.0, v86
	v_rcp_f32_e32 v85, v85
	v_pk_mul_f32 v[90:91], v[90:91], v[166:167] op_sel_hi:[1,0]
	v_mul_f32_e32 v82, v88, v82
	v_mul_f32_e32 v82, v82, v84
	v_mul_f32_e32 v83, v89, v83
	v_mul_f32_e32 v84, 0xbfb8aa3b, v90
	v_mul_f32_e32 v83, v83, v85
	v_exp_f32_e32 v84, v84
	v_mul_f32_e32 v85, 0xbfb8aa3b, v91
	v_exp_f32_e32 v85, v85
	v_cvt_pk_bf16_f32 v82, v82, v83
	v_add_f32_e32 v83, 1.0, v84
	v_rcp_f32_e32 v83, v83
	v_add_f32_e32 v84, 1.0, v85
	v_rcp_f32_e32 v84, v84
	v_rsq_f32_e32 v148, v163
	v_mul_f32_e32 v85, v90, v96
	v_mul_f32_e32 v83, v85, v83
	v_mul_f32_e32 v85, v91, v97
	v_add_u32_e32 v98, s11, v152
	v_mul_f32_e32 v84, v85, v84
	v_cvt_pk_bf16_f32 v83, v83, v84
	v_mad_i64_i32 v[84:85], s[20:21], v98, s48, v[112:113]
	v_lshl_add_u64 v[84:85], v[84:85], 0, v[114:115]
	v_pk_mul_f32 v[76:77], v[76:77], v[148:149] op_sel_hi:[1,0]
	global_store_dwordx4 v[84:85], v[80:83], off sc1
	v_pk_mul_f32 v[68:69], v[68:69], v[148:149] op_sel_hi:[1,0]
	v_pk_mul_f32 v[78:79], v[78:79], v[148:149] op_sel_hi:[1,0]
	v_pk_mul_f32 v[80:81], v[66:67], v[148:149] op_sel_hi:[1,0]
	v_mul_f32_e32 v66, 0xbfb8aa3b, v76
	v_exp_f32_e32 v83, v66
	v_mul_f32_e32 v66, 0xbfb8aa3b, v77
	v_exp_f32_e32 v84, v66
	v_pk_mul_f32 v[66:67], v[64:65], v[148:149] op_sel_hi:[1,0]
	v_add_f32_e32 v64, 1.0, v83
	v_rcp_f32_e32 v64, v64
	v_add_f32_e32 v65, 1.0, v84
	v_rcp_f32_e32 v65, v65
	v_mul_f32_e32 v68, v76, v68
	v_mul_f32_e32 v64, v68, v64
	v_mul_f32_e32 v68, v77, v69
	v_mul_f32_e32 v65, v68, v65
	v_mul_f32_e32 v68, 0xbfb8aa3b, v78
	v_exp_f32_e32 v68, v68
	v_mul_f32_e32 v69, 0xbfb8aa3b, v79
	v_exp_f32_e32 v69, v69
	v_cvt_pk_bf16_f32 v64, v64, v65
	v_add_f32_e32 v65, 1.0, v68
	v_rcp_f32_e32 v65, v65
	v_add_f32_e32 v68, 1.0, v69
	v_rcp_f32_e32 v68, v68
	v_pk_mul_f32 v[70:71], v[70:71], v[148:149] op_sel_hi:[1,0]
	v_pk_mul_f32 v[72:73], v[72:73], v[148:149] op_sel_hi:[1,0]
	v_mul_f32_e32 v69, v78, v70
	v_mul_f32_e32 v65, v69, v65
	v_mul_f32_e32 v69, v79, v71
	v_mul_f32_e32 v68, v69, v68
	v_mul_f32_e32 v69, 0xbfb8aa3b, v72
	v_exp_f32_e32 v69, v69
	v_mul_f32_e32 v70, 0xbfb8aa3b, v73
	v_exp_f32_e32 v70, v70
	v_cvt_pk_bf16_f32 v65, v65, v68
	v_add_f32_e32 v68, 1.0, v69
	v_rcp_f32_e32 v68, v68
	v_add_f32_e32 v69, 1.0, v70
	v_rcp_f32_e32 v69, v69
	v_pk_mul_f32 v[74:75], v[74:75], v[148:149] op_sel_hi:[1,0]
	v_mul_f32_e32 v66, v72, v66
	v_mul_f32_e32 v66, v66, v68
	v_mul_f32_e32 v67, v73, v67
	v_mul_f32_e32 v68, 0xbfb8aa3b, v74
	v_mul_f32_e32 v67, v67, v69
	v_exp_f32_e32 v68, v68
	v_mul_f32_e32 v69, 0xbfb8aa3b, v75
	v_exp_f32_e32 v69, v69
	v_cvt_pk_bf16_f32 v66, v66, v67
	v_add_f32_e32 v67, 1.0, v68
	v_rcp_f32_e32 v67, v67
	v_add_f32_e32 v68, 1.0, v69
	v_rcp_f32_e32 v68, v68
	v_mul_f32_e32 v69, v74, v80
	v_mul_f32_e32 v67, v69, v67
	v_mul_f32_e32 v69, v75, v81
	v_add_u32_e32 v82, s11, v153
	v_mul_f32_e32 v68, v69, v68
	v_cvt_pk_bf16_f32 v67, v67, v68
	v_mad_i64_i32 v[68:69], s[20:21], v82, s48, v[112:113]
	v_add_u32_e32 v88, 0x80, v146
	v_lshl_add_u64 v[68:69], v[68:69], 0, v[114:115]
	v_ashrrev_i32_e32 v89, 31, v88
	global_store_dwordx4 v[68:69], v[64:67], off sc1
	v_add_u32_e32 v70, 0x90, v146
	v_ashrrev_i32_e32 v71, 31, v70
	v_lshlrev_b64 v[64:65], 6, v[88:89]
	v_lshl_add_u64 v[64:65], v[136:137], 0, v[64:65]
	global_load_dwordx4 v[72:75], v[64:65], off
	v_lshlrev_b64 v[64:65], 6, v[70:71]
	v_lshl_add_u64 v[64:65], v[136:137], 0, v[64:65]
	global_load_dwordx4 v[76:79], v[64:65], off
	v_add_u32_e32 v66, 0xa0, v146
	v_ashrrev_i32_e32 v67, 31, v66
	v_lshlrev_b64 v[64:65], 6, v[66:67]
	v_lshl_add_u64 v[64:65], v[136:137], 0, v[64:65]
	global_load_dwordx4 v[80:83], v[64:65], off
	v_add_u32_e32 v64, 0xb0, v146
	v_ashrrev_i32_e32 v65, 31, v64
	v_lshlrev_b64 v[68:69], 6, v[64:65]
	v_lshl_add_u64 v[68:69], v[136:137], 0, v[68:69]
	global_load_dwordx4 v[84:87], v[68:69], off
	s_andn2_b64 vcc, exec, s[0:1]
	s_mov_b64 s[0:1], -1
	s_waitcnt vmcnt(3)
	v_mov_b32_e32 v68, v73
	v_mov_b32_e32 v69, v74
	v_mov_b32_e32 v73, v75
	v_pk_add_f32 v[68:69], v[68:69], v[72:73]
	s_nop 0
	v_add_f32_e32 v65, v68, v69
	ds_bpermute_b32 v67, v160, v65
	s_waitcnt vmcnt(2)
	v_mov_b32_e32 v68, v77
	v_mov_b32_e32 v69, v78
	v_mov_b32_e32 v77, v79
	v_pk_add_f32 v[68:69], v[68:69], v[76:77]
	s_waitcnt lgkmcnt(0)
	v_add_f32_e32 v65, v65, v67
	ds_bpermute_b32 v67, v147, v65
	v_add_f32_e32 v68, v68, v69
	ds_bpermute_b32 v69, v160, v68
	s_waitcnt lgkmcnt(1)
	v_add_f32_e32 v65, v65, v67
	v_fmamk_f32 v65, v65, 0x3a800000, v159
	v_rsq_f32_e32 v72, v65
	s_waitcnt lgkmcnt(0)
	v_add_f32_e32 v65, v68, v69
	s_waitcnt vmcnt(1)
	v_mov_b32_e32 v68, v81
	v_mov_b32_e32 v69, v82
	v_mov_b32_e32 v81, v83
	v_pk_add_f32 v[68:69], v[68:69], v[80:81]
	ds_bpermute_b32 v67, v147, v65
	v_add_f32_e32 v71, v68, v69
	s_waitcnt vmcnt(0)
	v_mov_b32_e32 v68, v85
	v_mov_b32_e32 v69, v86
	v_mov_b32_e32 v85, v87
	ds_bpermute_b32 v73, v160, v71
	v_pk_add_f32 v[68:69], v[68:69], v[84:85]
	s_waitcnt lgkmcnt(1)
	v_add_f32_e32 v65, v65, v67
	v_add_f32_e32 v68, v68, v69
	ds_bpermute_b32 v69, v160, v68
	s_waitcnt lgkmcnt(1)
	v_add_f32_e32 v67, v71, v73
	ds_bpermute_b32 v71, v147, v67
	v_fmamk_f32 v65, v65, 0x3a800000, v159
	v_rsq_f32_e32 v74, v65
	s_waitcnt lgkmcnt(1)
	v_add_f32_e32 v68, v68, v69
	ds_bpermute_b32 v69, v147, v68
	s_waitcnt lgkmcnt(1)
	v_add_f32_e32 v65, v67, v71
	v_fmamk_f32 v65, v65, 0x3a800000, v159
	v_rsq_f32_e32 v76, v65
	v_pk_mul_f32 v[60:61], v[60:61], v[72:73] op_sel_hi:[1,0]
	s_waitcnt lgkmcnt(0)
	v_add_f32_e32 v65, v68, v69
	v_fmamk_f32 v65, v65, 0x3a800000, v159
	v_pk_mul_f32 v[78:79], v[50:51], v[72:73] op_sel_hi:[1,0]
	v_mul_f32_e32 v50, 0xbfb8aa3b, v60
	v_rsq_f32_e32 v68, v65
	v_exp_f32_e32 v65, v50
	v_mul_f32_e32 v50, 0xbfb8aa3b, v61
	v_exp_f32_e32 v67, v50
	v_pk_mul_f32 v[50:51], v[48:49], v[72:73] op_sel_hi:[1,0]
	v_add_f32_e32 v48, 1.0, v65
	v_rcp_f32_e32 v48, v48
	v_add_f32_e32 v49, 1.0, v67
	v_rcp_f32_e32 v49, v49
	v_pk_mul_f32 v[52:53], v[52:53], v[72:73] op_sel_hi:[1,0]
	v_pk_mul_f32 v[62:63], v[62:63], v[72:73] op_sel_hi:[1,0]
	v_mul_f32_e32 v52, v60, v52
	v_mul_f32_e32 v48, v52, v48
	v_mul_f32_e32 v52, v61, v53
	v_mul_f32_e32 v49, v52, v49
	v_mul_f32_e32 v52, 0xbfb8aa3b, v62
	v_exp_f32_e32 v52, v52
	v_mul_f32_e32 v53, 0xbfb8aa3b, v63
	v_exp_f32_e32 v53, v53
	v_cvt_pk_bf16_f32 v48, v48, v49
	v_add_f32_e32 v49, 1.0, v52
	v_rcp_f32_e32 v49, v49
	v_add_f32_e32 v52, 1.0, v53
	v_rcp_f32_e32 v52, v52
	v_pk_mul_f32 v[54:55], v[54:55], v[72:73] op_sel_hi:[1,0]
	v_pk_mul_f32 v[56:57], v[56:57], v[72:73] op_sel_hi:[1,0]
	v_mul_f32_e32 v53, v62, v54
	v_mul_f32_e32 v49, v53, v49
	v_mul_f32_e32 v53, v63, v55
	v_mul_f32_e32 v52, v53, v52
	v_mul_f32_e32 v53, 0xbfb8aa3b, v56
	v_exp_f32_e32 v53, v53
	v_mul_f32_e32 v54, 0xbfb8aa3b, v57
	v_exp_f32_e32 v54, v54
	v_cvt_pk_bf16_f32 v49, v49, v52
	v_add_f32_e32 v52, 1.0, v53
	v_rcp_f32_e32 v52, v52
	v_add_f32_e32 v53, 1.0, v54
	v_rcp_f32_e32 v53, v53
	v_pk_mul_f32 v[58:59], v[58:59], v[72:73] op_sel_hi:[1,0]
	v_mul_f32_e32 v50, v56, v50
	v_mul_f32_e32 v50, v50, v52
	v_mul_f32_e32 v51, v57, v51
	v_mul_f32_e32 v52, 0xbfb8aa3b, v58
	v_mul_f32_e32 v51, v51, v53
	v_exp_f32_e32 v52, v52
	v_mul_f32_e32 v53, 0xbfb8aa3b, v59
	v_exp_f32_e32 v53, v53
	v_cvt_pk_bf16_f32 v50, v50, v51
	v_add_f32_e32 v51, 1.0, v52
	v_rcp_f32_e32 v51, v51
	v_add_f32_e32 v52, 1.0, v53
	v_rcp_f32_e32 v52, v52
	v_mul_f32_e32 v53, v58, v78
	v_mul_f32_e32 v51, v53, v51
	v_mul_f32_e32 v53, v59, v79
	v_mul_f32_e32 v52, v53, v52
	v_cvt_pk_bf16_f32 v51, v51, v52
	v_mad_i64_i32 v[52:53], s[20:21], v88, s48, v[112:113]
	v_lshl_add_u64 v[52:53], v[52:53], 0, v[114:115]
	v_pk_mul_f32 v[44:45], v[44:45], v[74:75] op_sel_hi:[1,0]
	global_store_dwordx4 v[52:53], v[48:51], off sc1
	v_pk_mul_f32 v[36:37], v[36:37], v[74:75] op_sel_hi:[1,0]
	v_pk_mul_f32 v[46:47], v[46:47], v[74:75] op_sel_hi:[1,0]
	v_pk_mul_f32 v[48:49], v[34:35], v[74:75] op_sel_hi:[1,0]
	v_mul_f32_e32 v34, 0xbfb8aa3b, v44
	v_exp_f32_e32 v50, v34
	v_mul_f32_e32 v34, 0xbfb8aa3b, v45
	v_exp_f32_e32 v51, v34
	v_pk_mul_f32 v[34:35], v[32:33], v[74:75] op_sel_hi:[1,0]
	v_add_f32_e32 v32, 1.0, v50
	v_rcp_f32_e32 v32, v32
	v_add_f32_e32 v33, 1.0, v51
	v_rcp_f32_e32 v33, v33
	v_mul_f32_e32 v36, v44, v36
	v_mul_f32_e32 v32, v36, v32
	v_mul_f32_e32 v36, v45, v37
	v_mul_f32_e32 v33, v36, v33
	v_mul_f32_e32 v36, 0xbfb8aa3b, v46
	v_exp_f32_e32 v36, v36
	v_mul_f32_e32 v37, 0xbfb8aa3b, v47
	v_exp_f32_e32 v37, v37
	v_cvt_pk_bf16_f32 v32, v32, v33
	v_add_f32_e32 v33, 1.0, v36
	v_rcp_f32_e32 v33, v33
	v_add_f32_e32 v36, 1.0, v37
	v_rcp_f32_e32 v36, v36
	v_pk_mul_f32 v[38:39], v[38:39], v[74:75] op_sel_hi:[1,0]
	v_pk_mul_f32 v[40:41], v[40:41], v[74:75] op_sel_hi:[1,0]
	v_mul_f32_e32 v37, v46, v38
	v_mul_f32_e32 v33, v37, v33
	v_mul_f32_e32 v37, v47, v39
	v_mul_f32_e32 v36, v37, v36
	v_mul_f32_e32 v37, 0xbfb8aa3b, v40
	v_exp_f32_e32 v37, v37
	v_mul_f32_e32 v38, 0xbfb8aa3b, v41
	v_exp_f32_e32 v38, v38
	v_cvt_pk_bf16_f32 v33, v33, v36
	v_add_f32_e32 v36, 1.0, v37
	v_rcp_f32_e32 v36, v36
	v_add_f32_e32 v37, 1.0, v38
	v_rcp_f32_e32 v37, v37
	v_pk_mul_f32 v[42:43], v[42:43], v[74:75] op_sel_hi:[1,0]
	v_mul_f32_e32 v34, v40, v34
	v_mul_f32_e32 v34, v34, v36
	v_mul_f32_e32 v35, v41, v35
	v_mul_f32_e32 v36, 0xbfb8aa3b, v42
	v_mul_f32_e32 v35, v35, v37
	v_exp_f32_e32 v36, v36
	v_mul_f32_e32 v37, 0xbfb8aa3b, v43
	v_exp_f32_e32 v37, v37
	v_cvt_pk_bf16_f32 v34, v34, v35
	v_add_f32_e32 v35, 1.0, v36
	v_rcp_f32_e32 v35, v35
	v_add_f32_e32 v36, 1.0, v37
	v_rcp_f32_e32 v36, v36
	v_mul_f32_e32 v37, v42, v48
	v_mul_f32_e32 v35, v37, v35
	v_mul_f32_e32 v37, v43, v49
	v_mul_f32_e32 v36, v37, v36
	v_cvt_pk_bf16_f32 v35, v35, v36
	v_mad_i64_i32 v[36:37], s[20:21], v70, s48, v[112:113]
	v_lshl_add_u64 v[36:37], v[36:37], 0, v[114:115]
	v_pk_mul_f32 v[28:29], v[28:29], v[76:77] op_sel_hi:[1,0]
	global_store_dwordx4 v[36:37], v[32:35], off sc1
	v_pk_mul_f32 v[20:21], v[20:21], v[76:77] op_sel_hi:[1,0]
	v_pk_mul_f32 v[30:31], v[30:31], v[76:77] op_sel_hi:[1,0]
	v_pk_mul_f32 v[32:33], v[18:19], v[76:77] op_sel_hi:[1,0]
	v_mul_f32_e32 v18, 0xbfb8aa3b, v28
	v_exp_f32_e32 v34, v18
	v_mul_f32_e32 v18, 0xbfb8aa3b, v29
	v_exp_f32_e32 v35, v18
	v_pk_mul_f32 v[18:19], v[16:17], v[76:77] op_sel_hi:[1,0]
	v_add_f32_e32 v16, 1.0, v34
	v_rcp_f32_e32 v16, v16
	v_add_f32_e32 v17, 1.0, v35
	v_rcp_f32_e32 v17, v17
	v_mul_f32_e32 v20, v28, v20
	v_mul_f32_e32 v16, v20, v16
	v_mul_f32_e32 v20, v29, v21
	v_mul_f32_e32 v17, v20, v17
	v_mul_f32_e32 v20, 0xbfb8aa3b, v30
	v_exp_f32_e32 v20, v20
	v_mul_f32_e32 v21, 0xbfb8aa3b, v31
	v_exp_f32_e32 v21, v21
	v_cvt_pk_bf16_f32 v16, v16, v17
	v_add_f32_e32 v17, 1.0, v20
	v_rcp_f32_e32 v17, v17
	v_add_f32_e32 v20, 1.0, v21
	v_rcp_f32_e32 v20, v20
	v_pk_mul_f32 v[22:23], v[22:23], v[76:77] op_sel_hi:[1,0]
	v_pk_mul_f32 v[24:25], v[24:25], v[76:77] op_sel_hi:[1,0]
	v_mul_f32_e32 v21, v30, v22
	v_mul_f32_e32 v17, v21, v17
	v_mul_f32_e32 v21, v31, v23
	v_mul_f32_e32 v20, v21, v20
	v_mul_f32_e32 v21, 0xbfb8aa3b, v24
	v_exp_f32_e32 v21, v21
	v_mul_f32_e32 v22, 0xbfb8aa3b, v25
	v_exp_f32_e32 v22, v22
	v_cvt_pk_bf16_f32 v17, v17, v20
	v_add_f32_e32 v20, 1.0, v21
	v_rcp_f32_e32 v20, v20
	v_add_f32_e32 v21, 1.0, v22
	v_rcp_f32_e32 v21, v21
	v_pk_mul_f32 v[26:27], v[26:27], v[76:77] op_sel_hi:[1,0]
	v_mul_f32_e32 v18, v24, v18
	v_mul_f32_e32 v18, v18, v20
	v_mul_f32_e32 v19, v25, v19
	v_mul_f32_e32 v20, 0xbfb8aa3b, v26
	v_mul_f32_e32 v19, v19, v21
	v_exp_f32_e32 v20, v20
	v_mul_f32_e32 v21, 0xbfb8aa3b, v27
	v_exp_f32_e32 v21, v21
	v_cvt_pk_bf16_f32 v18, v18, v19
	v_add_f32_e32 v19, 1.0, v20
	v_rcp_f32_e32 v19, v19
	v_add_f32_e32 v20, 1.0, v21
	v_rcp_f32_e32 v20, v20
	v_mul_f32_e32 v21, v26, v32
	v_mul_f32_e32 v19, v21, v19
	v_mul_f32_e32 v21, v27, v33
	v_mul_f32_e32 v20, v21, v20
	v_cvt_pk_bf16_f32 v19, v19, v20
	v_mad_i64_i32 v[20:21], s[20:21], v66, s48, v[112:113]
	v_lshl_add_u64 v[20:21], v[20:21], 0, v[114:115]
	v_pk_mul_f32 v[12:13], v[12:13], v[68:69] op_sel_hi:[1,0]
	global_store_dwordx4 v[20:21], v[16:19], off sc1
	v_pk_mul_f32 v[4:5], v[4:5], v[68:69] op_sel_hi:[1,0]
	v_pk_mul_f32 v[14:15], v[14:15], v[68:69] op_sel_hi:[1,0]
	v_pk_mul_f32 v[16:17], v[2:3], v[68:69] op_sel_hi:[1,0]
	v_mul_f32_e32 v2, 0xbfb8aa3b, v12
	v_exp_f32_e32 v18, v2
	v_mul_f32_e32 v2, 0xbfb8aa3b, v13
	v_exp_f32_e32 v19, v2
	v_pk_mul_f32 v[2:3], v[0:1], v[68:69] op_sel_hi:[1,0]
	v_add_f32_e32 v0, 1.0, v18
	v_rcp_f32_e32 v0, v0
	v_add_f32_e32 v1, 1.0, v19
	v_rcp_f32_e32 v1, v1
	v_mul_f32_e32 v4, v12, v4
	v_mul_f32_e32 v0, v4, v0
	v_mul_f32_e32 v4, v13, v5
	v_mul_f32_e32 v1, v4, v1
	v_mul_f32_e32 v4, 0xbfb8aa3b, v14
	v_exp_f32_e32 v4, v4
	v_mul_f32_e32 v5, 0xbfb8aa3b, v15
	v_exp_f32_e32 v5, v5
	v_cvt_pk_bf16_f32 v0, v0, v1
	v_add_f32_e32 v1, 1.0, v4
	v_rcp_f32_e32 v1, v1
	v_add_f32_e32 v4, 1.0, v5
	v_rcp_f32_e32 v4, v4
	v_pk_mul_f32 v[6:7], v[6:7], v[68:69] op_sel_hi:[1,0]
	v_pk_mul_f32 v[8:9], v[8:9], v[68:69] op_sel_hi:[1,0]
	v_mul_f32_e32 v5, v14, v6
	v_mul_f32_e32 v1, v5, v1
	v_mul_f32_e32 v5, v15, v7
	v_mul_f32_e32 v4, v5, v4
	v_mul_f32_e32 v5, 0xbfb8aa3b, v8
	v_exp_f32_e32 v5, v5
	v_mul_f32_e32 v6, 0xbfb8aa3b, v9
	v_exp_f32_e32 v6, v6
	v_cvt_pk_bf16_f32 v1, v1, v4
	v_add_f32_e32 v4, 1.0, v5
	v_rcp_f32_e32 v4, v4
	v_add_f32_e32 v5, 1.0, v6
	v_rcp_f32_e32 v5, v5
	v_pk_mul_f32 v[10:11], v[10:11], v[68:69] op_sel_hi:[1,0]
	v_mul_f32_e32 v2, v8, v2
	v_mul_f32_e32 v2, v2, v4
	v_mul_f32_e32 v3, v9, v3
	v_mul_f32_e32 v4, 0xbfb8aa3b, v10
	v_mul_f32_e32 v3, v3, v5
	v_exp_f32_e32 v4, v4
	v_mul_f32_e32 v5, 0xbfb8aa3b, v11
	v_exp_f32_e32 v5, v5
	v_cvt_pk_bf16_f32 v2, v2, v3
	v_add_f32_e32 v3, 1.0, v4
	v_rcp_f32_e32 v3, v3
	v_add_f32_e32 v4, 1.0, v5
	v_rcp_f32_e32 v4, v4
	v_mul_f32_e32 v5, v10, v16
	v_mul_f32_e32 v3, v5, v3
	v_mul_f32_e32 v5, v11, v17
	v_mul_f32_e32 v4, v5, v4
	v_cvt_pk_bf16_f32 v3, v3, v4
	v_mad_i64_i32 v[4:5], s[20:21], v64, s48, v[112:113]
	v_lshl_add_u64 v[4:5], v[4:5], 0, v[114:115]
	global_store_dwordx4 v[4:5], v[0:3], off sc1
	s_cbranch_vccnz .LBB0_2119
	s_andn2_b64 vcc, exec, s[4:5]
	s_cbranch_vccnz .LBB0_2118
	s_barrier
	s_branch .LBB0_2118
